# stack + MoBA prep: the 32 cross-row ds_bpermute exchanges per item replaced by v_permlane16_swap (no LDS round trip)
# baseline (speedup 1.0000x reference)
; __device__ __forceinline__ void phase_moba_prep(const Params& P, LAS unsigned char* lds, int l, int first, int stride) {
;     ...
;         const int h = it & 3, j = (it >> 2) & 15, b = it >> 6, bh = b * NH + h;
;         const int t0 = 256 * j + tg * 16;
;         const f16* base = p + ((size_t)(b * SEQ + t0)) * NIN + 128 * h + 4 * d4;
;         f16x4 raw[3][16];
; #pragma unroll
;         for (int w3 = 0; w3 < 3; ++w3)
; #pragma unroll
;             for (int i = 0; i < 16; ++i) raw[w3][i] = *(const f16x4*)(base + (3 + w3) * GW + (size_t)i * NIN);
; #pragma unroll
;         for (int which = 0; which < 2; ++which) {
;             const f32x4 gg = which == 0 ? gq : gk;
;             f16* dst = (which == 0 ? Q16 : K16) + ((size_t)bh * SEQ + t0) * HD + 4 * d4;
;             f32x4 v[16];
; #pragma unroll
;             for (int i = 0; i < 16; ++i) { const f16x4 t = raw[which][i]; v[i] = (f32x4){(float)t[0], (float)t[1], (float)t[2], (float)t[3]}; }
.LBB0_768:
	s_bfe_u32 s19, s18, 0x40002
	s_ashr_i32 s2, s18, 6
	v_lshl_add_u32 v16, s19, 8, v160
	s_and_b32 s0, s18, 3
	v_lshl_add_u32 v17, s2, 12, v16
	v_mov_b64_e32 v[18:19], s[90:91]
	s_lshl_b32 s1, s2, 2
	v_mad_i64_i32 v[18:19], s[2:3], v17, s51, v[18:19]
	s_lshl_b32 s56, s0, 8
	v_lshl_add_u64 v[18:19], v[18:19], 0, s[56:57]
	v_lshl_add_u64 v[48:49], v[18:19], 0, v[2:3]
	s_mov_b32 s2, 0x24ff1000
	v_add_co_u32_e32 v18, vcc, s2, v48
	s_mov_b32 s2, 0x24ff4000
	s_nop 0
	v_addc_co_u32_e32 v19, vcc, 0, v49, vcc
	v_add_co_u32_e32 v20, vcc, s2, v48
	s_mov_b32 s2, 0x24ff6000
	s_nop 0
	v_addc_co_u32_e32 v21, vcc, 0, v49, vcc
	v_add_co_u32_e32 v22, vcc, s2, v48
	s_mov_b32 s2, 0x24ff8000
	s_nop 0
	v_addc_co_u32_e32 v23, vcc, 0, v49, vcc
	global_load_dwordx2 v[84:85], v[18:19], off offset:3072
	global_load_dwordx2 v[86:87], v[22:23], off offset:1024
	v_add_co_u32_e32 v18, vcc, s2, v48
	s_mov_b32 s2, 0x24ffa000
	s_nop 0
	v_addc_co_u32_e32 v19, vcc, 0, v49, vcc
	v_add_co_u32_e32 v24, vcc, s2, v48
	s_mov_b32 s2, 0x24ffd000
	s_nop 0
	v_addc_co_u32_e32 v25, vcc, 0, v49, vcc
	v_add_co_u32_e32 v28, vcc, s2, v48
	s_mov_b32 s2, 0x24fff000
	s_nop 0
	v_addc_co_u32_e32 v29, vcc, 0, v49, vcc
	v_add_co_u32_e32 v30, vcc, s2, v48
	s_mov_b32 s2, 0x25001000
	s_nop 0
	v_addc_co_u32_e32 v31, vcc, 0, v49, vcc
	global_load_dwordx2 v[90:91], v[24:25], off offset:3072
	global_load_dwordx2 v[94:95], v[28:29], off
	v_add_co_u32_e32 v24, vcc, s2, v48
	s_mov_b32 s2, 0x25003000
	s_nop 0
	v_addc_co_u32_e32 v25, vcc, 0, v49, vcc
	v_add_co_u32_e32 v26, vcc, s2, v48
	s_mov_b32 s2, 0x25006000
	s_nop 0
	v_addc_co_u32_e32 v27, vcc, 0, v49, vcc
	v_add_co_u32_e32 v34, vcc, s2, v48
	s_mov_b32 s2, 0x25008000
	s_nop 0
	v_addc_co_u32_e32 v35, vcc, 0, v49, vcc
	v_add_co_u32_e32 v36, vcc, s2, v48
	s_mov_b32 s2, 0x2500a000
	s_nop 0
	v_addc_co_u32_e32 v37, vcc, 0, v49, vcc
	global_load_dwordx2 v[98:99], v[30:31], off offset:1024
	global_load_dwordx2 v[102:103], v[34:35], off
	global_load_dwordx2 v[100:101], v[26:27], off offset:3072
	v_add_co_u32_e32 v26, vcc, s2, v48
	s_mov_b32 s2, 0x2500c000
	s_nop 0
	v_addc_co_u32_e32 v27, vcc, 0, v49, vcc
	v_add_co_u32_e32 v32, vcc, s2, v48
	global_load_dwordx2 v[88:89], v[20:21], off
	global_load_dwordx2 v[96:97], v[24:25], off offset:2048
	global_load_dwordx2 v[144:145], v[26:27], off offset:2048
	global_load_dwordx2 v[92:93], v[18:19], off offset:2048
	v_addc_co_u32_e32 v33, vcc, 0, v49, vcc
	global_load_dwordx2 v[142:143], v[32:33], off offset:3072
	global_load_dwordx2 v[104:105], v[36:37], off offset:1024
	s_mov_b32 s2, 0x2500f000
	v_add_co_u32_e32 v44, vcc, s2, v48
	s_mov_b32 s2, 0x25011000
	s_nop 0
	v_addc_co_u32_e32 v45, vcc, 0, v49, vcc
	v_add_co_u32_e32 v46, vcc, s2, v48
	s_mov_b32 s2, 0x25013000
	s_nop 0
	v_addc_co_u32_e32 v47, vcc, 0, v49, vcc
	global_load_dwordx2 v[146:147], v[44:45], off
	v_add_co_u32_e32 v32, vcc, s2, v48
	s_mov_b32 s2, 0x24ff2000
	s_nop 0
	v_addc_co_u32_e32 v33, vcc, 0, v49, vcc
	v_add_co_u32_e32 v38, vcc, s2, v48
	s_waitcnt vmcnt(13)
	v_cvt_f32_f16_e32 v156, v84
	v_cvt_f32_f16_sdwa v157, v84 dst_sel:DWORD dst_unused:UNUSED_PAD src0_sel:WORD_1
	v_cvt_f32_f16_e32 v158, v85
	v_cvt_f32_f16_sdwa v159, v85 dst_sel:DWORD dst_unused:UNUSED_PAD src0_sel:WORD_1
	v_addc_co_u32_e32 v39, vcc, 0, v49, vcc
	s_mov_b32 s2, 0x24ffb000
	v_add_co_u32_e32 v40, vcc, s2, v48
	s_mov_b32 s2, 0x25004000
	s_nop 0
	v_addc_co_u32_e32 v41, vcc, 0, v49, vcc
	v_add_co_u32_e32 v42, vcc, s2, v48
	s_mov_b32 s2, 0x2500d000
	s_nop 0
	v_addc_co_u32_e32 v43, vcc, 0, v49, vcc
	v_add_co_u32_e32 v82, vcc, s2, v48
	s_mov_b32 s2, 0x24ff9000
	s_nop 0
	v_addc_co_u32_e32 v83, vcc, 0, v49, vcc
	global_load_dwordx2 v[148:149], v[46:47], off offset:1024
	global_load_dwordx2 v[150:151], v[32:33], off offset:2048
	global_load_dwordx2 v[70:71], v[38:39], off
	global_load_dwordx2 v[62:63], v[20:21], off offset:1024
	global_load_dwordx2 v[54:55], v[22:23], off offset:2048
	global_load_dwordx2 v[52:53], v[18:19], off offset:3072
	global_load_dwordx2 v[50:51], v[40:41], off
	global_load_dwordx2 v[74:75], v[28:29], off offset:1024
	global_load_dwordx2 v[66:67], v[30:31], off offset:2048
	global_load_dwordx2 v[80:81], v[24:25], off offset:3072
	v_add_co_u32_e32 v24, vcc, s2, v48
	s_mov_b32 s2, 0x25002000
	s_nop 0
	v_addc_co_u32_e32 v25, vcc, 0, v49, vcc
	global_load_dwordx2 v[78:79], v[42:43], off
	global_load_dwordx2 v[76:77], v[34:35], off offset:1024
	global_load_dwordx2 v[68:69], v[36:37], off offset:2048
	global_load_dwordx2 v[58:59], v[26:27], off offset:3072
	global_load_dwordx2 v[72:73], v[82:83], off
	global_load_dwordx2 v[64:65], v[44:45], off offset:1024
	global_load_dwordx2 v[60:61], v[46:47], off offset:2048
	global_load_dwordx2 v[56:57], v[32:33], off offset:3072
	global_load_dwordx2 v[18:19], v[38:39], off offset:1024
	s_nop 0
	global_load_dwordx2 v[20:21], v[20:21], off offset:2048
	s_nop 0
	global_load_dwordx2 v[22:23], v[22:23], off offset:3072
	s_nop 0
	global_load_dwordx2 v[24:25], v[24:25], off
	s_nop 0
	global_load_dwordx2 v[26:27], v[40:41], off offset:1024
	s_nop 0
	global_load_dwordx2 v[28:29], v[28:29], off offset:2048
	s_nop 0
	global_load_dwordx2 v[32:33], v[30:31], off offset:3072
	v_add_co_u32_e32 v30, vcc, s2, v48
	s_mov_b32 s2, 0x2500b000
	s_nop 0
	v_addc_co_u32_e32 v31, vcc, 0, v49, vcc
	v_add_co_u32_e32 v38, vcc, s2, v48
	s_mov_b32 s2, 0x25014000
	s_nop 0
	v_addc_co_u32_e32 v39, vcc, 0, v49, vcc
	s_waitcnt vmcnt(34)
	v_cvt_f32_f16_e32 v122, v98
	v_cvt_f32_f16_sdwa v123, v98 dst_sel:DWORD dst_unused:UNUSED_PAD src0_sel:WORD_1
	v_cvt_f32_f16_e32 v124, v99
	v_cvt_f32_f16_sdwa v125, v99 dst_sel:DWORD dst_unused:UNUSED_PAD src0_sel:WORD_1
	s_waitcnt vmcnt(32)
; __device__ __forceinline__ void phase_moba_prep(const Params& P, LAS unsigned char* lds, int l, int first, int stride) {
;     ...
;             for (int i = 0; i < 16; ++i) { const f16x4 t = raw[which][i]; v[i] = (f32x4){(float)t[0], (float)t[1], (float)t[2], (float)t[3]}; }
;             f32x4 cs = {0, 0, 0, 0};
; #pragma unroll
;             for (int i = 0; i < 16; ++i) {
;                 float ss = v[i][0] * v[i][0] + v[i][1] * v[i][1] + v[i][2] * v[i][2] + v[i][3] * v[i][3];
;                 ss = row_sum16(ss); ss += __shfl_xor(ss, 16);
;                 const float rstd = 1.0f / sqrtf(ss * (1.0f / HD) + EPS);
;                 f32x4 y = (v[i] * rstd) * gg;
;                 cs += y;
;                 if (which == 0) y = y * (0.08838834764831845f * 1.4426950408889634f);
;                 f16x4 o; o[0] = (f16)y[0]; o[1] = (f16)y[1]; o[2] = (f16)y[2]; o[3] = (f16)y[3];
;                 *(f16x4*)(dst + (size_t)i * HD) = o;
	v_cvt_f32_f16_e32 v114, v100
	v_cvt_f32_f16_sdwa v115, v100 dst_sel:DWORD dst_unused:UNUSED_PAD src0_sel:WORD_1
	v_cvt_f32_f16_e32 v116, v101
	v_cvt_f32_f16_sdwa v117, v101 dst_sel:DWORD dst_unused:UNUSED_PAD src0_sel:WORD_1
	v_add_co_u32_e32 v48, vcc, s2, v48
	s_or_b32 s12, s1, s0
	s_nop 0
	v_addc_co_u32_e32 v49, vcc, 0, v49, vcc
	s_waitcnt vmcnt(28)
	v_cvt_f32_f16_e32 v134, v92
	v_cvt_f32_f16_sdwa v135, v92 dst_sel:DWORD dst_unused:UNUSED_PAD src0_sel:WORD_1
	v_cvt_f32_f16_e32 v136, v93
	v_cvt_f32_f16_sdwa v137, v93 dst_sel:DWORD dst_unused:UNUSED_PAD src0_sel:WORD_1
	v_pk_mul_f32 v[92:93], v[156:157], v[156:157]
	s_waitcnt vmcnt(27)
	v_cvt_f32_f16_e32 v98, v142
	v_cvt_f32_f16_sdwa v99, v142 dst_sel:DWORD dst_unused:UNUSED_PAD src0_sel:WORD_1
	v_cvt_f32_f16_e32 v100, v143
	v_cvt_f32_f16_sdwa v101, v143 dst_sel:DWORD dst_unused:UNUSED_PAD src0_sel:WORD_1
	v_pk_mul_f32 v[142:143], v[158:159], v[158:159]
	v_add_f32_e32 v92, v92, v93
	v_add_f32_e32 v92, v142, v92
	v_add_f32_e32 v92, v143, v92
	s_ashr_i32 s13, s12, 31
	s_lshl_b64 s[0:1], s[12:13], 20
	v_add_f32_dpp v92, v92, v92 quad_perm:[1,0,3,2] row_mask:0xf bank_mask:0xf bound_ctrl:1
	v_ashrrev_i32_e32 v17, 31, v16
	s_add_u32 s2, s90, s0
	v_add_f32_dpp v92, v92, v92 quad_perm:[2,3,0,1] row_mask:0xf bank_mask:0xf bound_ctrl:1
	global_load_dwordx2 v[40:41], v[30:31], off
	s_nop 0
	global_load_dwordx2 v[30:31], v[42:43], off offset:1024
	s_nop 0
	global_load_dwordx2 v[34:35], v[34:35], off offset:2048
	s_nop 0
	global_load_dwordx2 v[36:37], v[36:37], off offset:3072
	v_add_f32_dpp v92, v92, v92 row_half_mirror row_mask:0xf bank_mask:0xf bound_ctrl:1
	global_load_dwordx2 v[38:39], v[38:39], off
	s_nop 0
	global_load_dwordx2 v[42:43], v[82:83], off offset:1024
	s_nop 0
	global_load_dwordx2 v[44:45], v[44:45], off offset:2048
	s_nop 0
	global_load_dwordx2 v[46:47], v[46:47], off offset:3072
	v_add_f32_dpp v92, v92, v92 row_mirror row_mask:0xf bank_mask:0xf bound_ctrl:1
	v_mov_b32_e32 v93, v92
	s_addc_u32 s3, s91, s1
	v_lshlrev_b64 v[82:83], 8, v[16:17]
	v_lshl_add_u64 v[82:83], s[2:3], 0, v[82:83]
	v_cvt_f32_f16_e32 v110, v102
	s_waitcnt lgkmcnt(0)
	s_nop 1
	v_permlane16_swap_b32_e32 v92, v93
	v_add_f32_e32 v92, v92, v93
	v_fmamk_f32 v92, v92, 0x3c000000, v234
	v_cmp_gt_f32_e32 vcc, s83, v92
	v_mul_f32_e32 v93, 0x4f800000, v92
	v_cvt_f32_f16_sdwa v111, v102 dst_sel:DWORD dst_unused:UNUSED_PAD src0_sel:WORD_1
	v_cndmask_b32_e32 v92, v92, v93, vcc
	v_sqrt_f32_e32 v93, v92
	v_cvt_f32_f16_e32 v112, v103
	v_cvt_f32_f16_sdwa v113, v103 dst_sel:DWORD dst_unused:UNUSED_PAD src0_sel:WORD_1
	v_cvt_f32_f16_e32 v102, v144
	v_add_u32_e32 v142, -1, v93
	v_fma_f32 v143, -v142, v93, v92
	v_cmp_ge_f32_e64 s[44:45], 0, v143
	v_add_u32_e32 v143, 1, v93
	v_cvt_f32_f16_sdwa v103, v144 dst_sel:DWORD dst_unused:UNUSED_PAD src0_sel:WORD_1
	v_cndmask_b32_e64 v142, v93, v142, s[44:45]
	v_fma_f32 v93, -v143, v93, v92
	v_cmp_lt_f32_e64 s[44:45], 0, v93
	s_waitcnt vmcnt(34)
	v_cvt_f32_f16_e32 v106, v104
	v_cvt_f32_f16_sdwa v107, v104 dst_sel:DWORD dst_unused:UNUSED_PAD src0_sel:WORD_1
	v_cndmask_b32_e64 v93, v142, v143, s[44:45]
	v_mul_f32_e32 v142, 0x37800000, v93
	v_cndmask_b32_e32 v93, v93, v142, vcc
	v_cmp_class_f32_e32 vcc, v92, v235
	v_cvt_f32_f16_e32 v108, v105
	v_cvt_f32_f16_sdwa v109, v105 dst_sel:DWORD dst_unused:UNUSED_PAD src0_sel:WORD_1
	v_cndmask_b32_e32 v92, v93, v92, vcc
	v_div_scale_f32 v93, s[2:3], v92, v92, 1.0
	v_rcp_f32_e32 v142, v93
	v_cvt_f32_f16_e32 v104, v145
	v_cvt_f32_f16_sdwa v105, v145 dst_sel:DWORD dst_unused:UNUSED_PAD src0_sel:WORD_1
	v_cvt_f32_f16_e32 v152, v88
	v_fma_f32 v143, -v93, v142, 1.0
	v_fmac_f32_e32 v142, v143, v142
	v_div_scale_f32 v143, vcc, 1.0, v92, 1.0
	v_mul_f32_e32 v144, v143, v142
	v_fma_f32 v145, -v93, v144, v143
	v_fmac_f32_e32 v144, v145, v142
	v_fma_f32 v93, -v93, v144, v143
	v_div_fmas_f32 v93, v93, v142, v144
	v_div_fixup_f32 v92, v93, v92, 1.0
	v_pk_mul_f32 v[142:143], v[158:159], v[92:93] op_sel_hi:[1,0]
	v_pk_mul_f32 v[92:93], v[156:157], v[92:93] op_sel_hi:[1,0]
	v_cvt_f32_f16_sdwa v153, v88 dst_sel:DWORD dst_unused:UNUSED_PAD src0_sel:WORD_1
	v_pk_mul_f32 v[92:93], v[4:5], v[92:93]
	v_pk_mul_f32 v[142:143], v[6:7], v[142:143]
	v_lshl_add_u64 v[82:83], v[82:83], 0, v[2:3]
	v_cvt_f32_f16_e32 v154, v89
	v_cvt_f32_f16_sdwa v155, v89 dst_sel:DWORD dst_unused:UNUSED_PAD src0_sel:WORD_1
	v_pk_mul_f32 v[142:143], v[142:143], s[36:37] op_sel_hi:[1,0]
	v_pk_mul_f32 v[92:93], v[92:93], s[36:37] op_sel_hi:[1,0]
	s_mov_b32 s2, 0x3dff1000
	v_cvt_pk_f16_f32 v143, v142, v143
	v_cvt_pk_f16_f32 v142, v92, v93
	v_add_co_u32_e32 v92, vcc, s2, v82
	global_load_dwordx2 v[48:49], v[48:49], off
	s_nop 0
	v_addc_co_u32_e32 v93, vcc, 0, v83, vcc
	global_store_dwordx2 v[92:93], v[142:143], off
	v_pk_mul_f32 v[142:143], v[152:153], v[152:153]
	v_pk_mul_f32 v[144:145], v[154:155], v[154:155]
	v_add_f32_e32 v142, v142, v143
	v_add_f32_e32 v142, v144, v142
	v_add_f32_e32 v142, v145, v142
	v_cvt_f32_f16_e32 v126, v94
	v_cvt_f32_f16_sdwa v127, v94 dst_sel:DWORD dst_unused:UNUSED_PAD src0_sel:WORD_1
	v_add_f32_dpp v142, v142, v142 quad_perm:[1,0,3,2] row_mask:0xf bank_mask:0xf bound_ctrl:1
	v_cvt_f32_f16_e32 v128, v95
	v_cvt_f32_f16_sdwa v129, v95 dst_sel:DWORD dst_unused:UNUSED_PAD src0_sel:WORD_1
	v_add_f32_dpp v142, v142, v142 quad_perm:[2,3,0,1] row_mask:0xf bank_mask:0xf bound_ctrl:1
	s_waitcnt vmcnt(35)
; __device__ __forceinline__ void phase_moba_prep(const Params& P, LAS unsigned char* lds, int l, int first, int stride) {
;     ...
;             for (int i = 0; i < 16; ++i) { const f16x4 t = raw[which][i]; v[i] = (f32x4){(float)t[0], (float)t[1], (float)t[2], (float)t[3]}; }
;             f32x4 cs = {0, 0, 0, 0};
; #pragma unroll
;             for (int i = 0; i < 16; ++i) {
;                 float ss = v[i][0] * v[i][0] + v[i][1] * v[i][1] + v[i][2] * v[i][2] + v[i][3] * v[i][3];
;                 ss = row_sum16(ss); ss += __shfl_xor(ss, 16);
;                 const float rstd = 1.0f / sqrtf(ss * (1.0f / HD) + EPS);
;                 f32x4 y = (v[i] * rstd) * gg;
;                 cs += y;
;                 if (which == 0) y = y * (0.08838834764831845f * 1.4426950408889634f);
;                 f16x4 o; o[0] = (f16)y[0]; o[1] = (f16)y[1]; o[2] = (f16)y[2]; o[3] = (f16)y[3];
;                 *(f16x4*)(dst + (size_t)i * HD) = o;
	v_cvt_f32_f16_e32 v94, v146
	v_cvt_f32_f16_sdwa v95, v146 dst_sel:DWORD dst_unused:UNUSED_PAD src0_sel:WORD_1
	v_add_f32_dpp v142, v142, v142 row_half_mirror row_mask:0xf bank_mask:0xf bound_ctrl:1
	v_cvt_f32_f16_e32 v118, v96
	v_cvt_f32_f16_sdwa v119, v96 dst_sel:DWORD dst_unused:UNUSED_PAD src0_sel:WORD_1
	v_add_f32_dpp v142, v142, v142 row_mirror row_mask:0xf bank_mask:0xf bound_ctrl:1
	v_mov_b32_e32 v143, v142
	v_cvt_f32_f16_e32 v120, v97
	v_cvt_f32_f16_sdwa v121, v97 dst_sel:DWORD dst_unused:UNUSED_PAD src0_sel:WORD_1
	v_cvt_f32_f16_e32 v96, v147
	v_cvt_f32_f16_sdwa v97, v147 dst_sel:DWORD dst_unused:UNUSED_PAD src0_sel:WORD_1
	s_waitcnt lgkmcnt(0)
	s_nop 1
	v_permlane16_swap_b32_e32 v142, v143
	v_add_f32_e32 v142, v142, v143
	v_fmamk_f32 v142, v142, 0x3c000000, v234
	v_cmp_gt_f32_e32 vcc, s83, v142
	v_mul_f32_e32 v143, 0x4f800000, v142
	v_cvt_f32_f16_e32 v138, v86
	v_cndmask_b32_e32 v142, v142, v143, vcc
	v_sqrt_f32_e32 v143, v142
	v_cvt_f32_f16_sdwa v139, v86 dst_sel:DWORD dst_unused:UNUSED_PAD src0_sel:WORD_1
	v_cvt_f32_f16_e32 v140, v87
	v_cvt_f32_f16_sdwa v141, v87 dst_sel:DWORD dst_unused:UNUSED_PAD src0_sel:WORD_1
	v_add_u32_e32 v144, -1, v143
	v_fma_f32 v145, -v144, v143, v142
	v_cmp_ge_f32_e64 s[44:45], 0, v145
	v_add_u32_e32 v145, 1, v143
	v_cvt_f32_f16_e32 v130, v90
	v_cndmask_b32_e64 v144, v143, v144, s[44:45]
	v_fma_f32 v143, -v145, v143, v142
	v_cmp_lt_f32_e64 s[44:45], 0, v143
	v_cvt_f32_f16_sdwa v131, v90 dst_sel:DWORD dst_unused:UNUSED_PAD src0_sel:WORD_1
	v_cvt_f32_f16_e32 v132, v91
	v_cndmask_b32_e64 v143, v144, v145, s[44:45]
	v_mul_f32_e32 v144, 0x37800000, v143
	v_cndmask_b32_e32 v143, v143, v144, vcc
	v_cmp_class_f32_e32 vcc, v142, v235
	v_cvt_f32_f16_sdwa v133, v91 dst_sel:DWORD dst_unused:UNUSED_PAD src0_sel:WORD_1
	s_waitcnt vmcnt(34)
	v_cvt_f32_f16_e32 v88, v148
	v_cndmask_b32_e32 v142, v143, v142, vcc
	v_div_scale_f32 v143, s[2:3], v142, v142, 1.0
	v_rcp_f32_e32 v144, v143
	v_cvt_f32_f16_sdwa v89, v148 dst_sel:DWORD dst_unused:UNUSED_PAD src0_sel:WORD_1
	v_cvt_f32_f16_e32 v90, v149
	v_cvt_f32_f16_sdwa v91, v149 dst_sel:DWORD dst_unused:UNUSED_PAD src0_sel:WORD_1
	v_fma_f32 v145, -v143, v144, 1.0
	v_fmac_f32_e32 v144, v145, v144
	v_div_scale_f32 v145, vcc, 1.0, v142, 1.0
	v_mul_f32_e32 v146, v145, v144
	v_fma_f32 v147, -v143, v146, v145
	v_fmac_f32_e32 v146, v147, v144
	v_fma_f32 v143, -v143, v146, v145
	v_div_fmas_f32 v143, v143, v144, v146
	v_div_fixup_f32 v142, v143, v142, 1.0
	v_pk_mul_f32 v[144:145], v[154:155], v[142:143] op_sel_hi:[1,0]
	v_pk_mul_f32 v[142:143], v[152:153], v[142:143] op_sel_hi:[1,0]
	v_pk_mul_f32 v[144:145], v[6:7], v[144:145]
	v_pk_mul_f32 v[142:143], v[4:5], v[142:143]
	v_pk_mul_f32 v[144:145], v[144:145], s[36:37] op_sel_hi:[1,0]
	v_pk_mul_f32 v[142:143], v[142:143], s[36:37] op_sel_hi:[1,0]
	v_cvt_pk_f16_f32 v145, v144, v145
	v_cvt_pk_f16_f32 v144, v142, v143
	v_pk_mul_f32 v[142:143], v[138:139], v[138:139]
	global_store_dwordx2 v[92:93], v[144:145], off offset:256
	v_pk_mul_f32 v[144:145], v[140:141], v[140:141]
	v_add_f32_e32 v142, v142, v143
	v_add_f32_e32 v142, v144, v142
	v_add_f32_e32 v142, v145, v142
	s_waitcnt vmcnt(34)
	v_cvt_f32_f16_e32 v84, v150
	v_cvt_f32_f16_sdwa v85, v150 dst_sel:DWORD dst_unused:UNUSED_PAD src0_sel:WORD_1
	v_add_f32_dpp v142, v142, v142 quad_perm:[1,0,3,2] row_mask:0xf bank_mask:0xf bound_ctrl:1
	v_cvt_f32_f16_e32 v86, v151
	v_cvt_f32_f16_sdwa v87, v151 dst_sel:DWORD dst_unused:UNUSED_PAD src0_sel:WORD_1
	v_add_f32_dpp v142, v142, v142 quad_perm:[2,3,0,1] row_mask:0xf bank_mask:0xf bound_ctrl:1
	s_nop 1
	v_add_f32_dpp v142, v142, v142 row_half_mirror row_mask:0xf bank_mask:0xf bound_ctrl:1
	s_nop 1
	v_add_f32_dpp v142, v142, v142 row_mirror row_mask:0xf bank_mask:0xf bound_ctrl:1
	v_mov_b32_e32 v143, v142
	s_waitcnt lgkmcnt(0)
	s_nop 1
	v_permlane16_swap_b32_e32 v142, v143
	v_add_f32_e32 v142, v142, v143
	v_fmamk_f32 v142, v142, 0x3c000000, v234
	v_cmp_gt_f32_e32 vcc, s83, v142
	v_mul_f32_e32 v143, 0x4f800000, v142
	s_nop 0
	v_cndmask_b32_e32 v142, v142, v143, vcc
	v_sqrt_f32_e32 v143, v142
	s_nop 0
	v_add_u32_e32 v144, -1, v143
	v_fma_f32 v145, -v144, v143, v142
	v_cmp_ge_f32_e64 s[44:45], 0, v145
	v_add_u32_e32 v145, 1, v143
	s_nop 0
	v_cndmask_b32_e64 v144, v143, v144, s[44:45]
	v_fma_f32 v143, -v145, v143, v142
	v_cmp_lt_f32_e64 s[44:45], 0, v143
	s_nop 1
	v_cndmask_b32_e64 v143, v144, v145, s[44:45]
	v_mul_f32_e32 v144, 0x37800000, v143
	v_cndmask_b32_e32 v143, v143, v144, vcc
	v_cmp_class_f32_e32 vcc, v142, v235
	s_nop 1
	v_cndmask_b32_e32 v142, v143, v142, vcc
	v_div_scale_f32 v143, s[2:3], v142, v142, 1.0
	v_rcp_f32_e32 v144, v143
	s_nop 0
	v_fma_f32 v145, -v143, v144, 1.0
	v_fmac_f32_e32 v144, v145, v144
	v_div_scale_f32 v145, vcc, 1.0, v142, 1.0
	v_mul_f32_e32 v146, v145, v144
	v_fma_f32 v147, -v143, v146, v145
	v_fmac_f32_e32 v146, v147, v144
	v_fma_f32 v143, -v143, v146, v145
	v_div_fmas_f32 v143, v143, v144, v146
	v_div_fixup_f32 v142, v143, v142, 1.0
	v_pk_mul_f32 v[140:141], v[140:141], v[142:143] op_sel_hi:[1,0]
	v_pk_mul_f32 v[138:139], v[138:139], v[142:143] op_sel_hi:[1,0]
	v_pk_mul_f32 v[140:141], v[6:7], v[140:141]
	v_pk_mul_f32 v[138:139], v[4:5], v[138:139]
	v_pk_mul_f32 v[140:141], v[140:141], s[36:37] op_sel_hi:[1,0]
	v_pk_mul_f32 v[138:139], v[138:139], s[36:37] op_sel_hi:[1,0]
	v_cvt_pk_f16_f32 v141, v140, v141
	v_cvt_pk_f16_f32 v140, v138, v139
	v_pk_mul_f32 v[138:139], v[134:135], v[134:135]
	global_store_dwordx2 v[92:93], v[140:141], off offset:512
	v_pk_mul_f32 v[140:141], v[136:137], v[136:137]
	v_add_f32_e32 v138, v138, v139
	v_add_f32_e32 v138, v140, v138
	v_add_f32_e32 v138, v141, v138
	s_nop 1
	v_add_f32_dpp v138, v138, v138 quad_perm:[1,0,3,2] row_mask:0xf bank_mask:0xf bound_ctrl:1
	s_nop 1
	v_add_f32_dpp v138, v138, v138 quad_perm:[2,3,0,1] row_mask:0xf bank_mask:0xf bound_ctrl:1
	s_nop 1
	v_add_f32_dpp v138, v138, v138 row_half_mirror row_mask:0xf bank_mask:0xf bound_ctrl:1
	s_nop 1
	v_add_f32_dpp v138, v138, v138 row_mirror row_mask:0xf bank_mask:0xf bound_ctrl:1
	v_mov_b32_e32 v139, v138
	s_waitcnt lgkmcnt(0)
; __device__ __forceinline__ void phase_moba_prep(const Params& P, LAS unsigned char* lds, int l, int first, int stride) {
;     ...
;             for (int i = 0; i < 16; ++i) { const f16x4 t = raw[which][i]; v[i] = (f32x4){(float)t[0], (float)t[1], (float)t[2], (float)t[3]}; }
;             f32x4 cs = {0, 0, 0, 0};
; #pragma unroll
;             for (int i = 0; i < 16; ++i) {
;                 float ss = v[i][0] * v[i][0] + v[i][1] * v[i][1] + v[i][2] * v[i][2] + v[i][3] * v[i][3];
;                 ss = row_sum16(ss); ss += __shfl_xor(ss, 16);
;                 const float rstd = 1.0f / sqrtf(ss * (1.0f / HD) + EPS);
;                 f32x4 y = (v[i] * rstd) * gg;
;                 cs += y;
;                 if (which == 0) y = y * (0.08838834764831845f * 1.4426950408889634f);
;                 f16x4 o; o[0] = (f16)y[0]; o[1] = (f16)y[1]; o[2] = (f16)y[2]; o[3] = (f16)y[3];
;                 *(f16x4*)(dst + (size_t)i * HD) = o;
	s_nop 1
	v_permlane16_swap_b32_e32 v138, v139
	v_add_f32_e32 v138, v138, v139
	v_fmamk_f32 v138, v138, 0x3c000000, v234
	v_cmp_gt_f32_e32 vcc, s83, v138
	v_mul_f32_e32 v139, 0x4f800000, v138
	s_nop 0
	v_cndmask_b32_e32 v138, v138, v139, vcc
	v_sqrt_f32_e32 v139, v138
	s_nop 0
	v_add_u32_e32 v140, -1, v139
	v_fma_f32 v141, -v140, v139, v138
	v_cmp_ge_f32_e64 s[44:45], 0, v141
	v_add_u32_e32 v141, 1, v139
	s_nop 0
	v_cndmask_b32_e64 v140, v139, v140, s[44:45]
	v_fma_f32 v139, -v141, v139, v138
	v_cmp_lt_f32_e64 s[44:45], 0, v139
	s_nop 1
	v_cndmask_b32_e64 v139, v140, v141, s[44:45]
	v_mul_f32_e32 v140, 0x37800000, v139
	v_cndmask_b32_e32 v139, v139, v140, vcc
	v_cmp_class_f32_e32 vcc, v138, v235
	s_nop 1
	v_cndmask_b32_e32 v138, v139, v138, vcc
	v_div_scale_f32 v139, s[2:3], v138, v138, 1.0
	v_rcp_f32_e32 v140, v139
	s_nop 0
	v_fma_f32 v141, -v139, v140, 1.0
	v_fmac_f32_e32 v140, v141, v140
	v_div_scale_f32 v141, vcc, 1.0, v138, 1.0
	v_mul_f32_e32 v142, v141, v140
	v_fma_f32 v143, -v139, v142, v141
	v_fmac_f32_e32 v142, v143, v140
	v_fma_f32 v139, -v139, v142, v141
	v_div_fmas_f32 v139, v139, v140, v142
	v_div_fixup_f32 v138, v139, v138, 1.0
	v_pk_mul_f32 v[136:137], v[136:137], v[138:139] op_sel_hi:[1,0]
	v_pk_mul_f32 v[134:135], v[134:135], v[138:139] op_sel_hi:[1,0]
	v_pk_mul_f32 v[136:137], v[6:7], v[136:137]
	v_pk_mul_f32 v[134:135], v[4:5], v[134:135]
	v_pk_mul_f32 v[136:137], v[136:137], s[36:37] op_sel_hi:[1,0]
	v_pk_mul_f32 v[134:135], v[134:135], s[36:37] op_sel_hi:[1,0]
	v_cvt_pk_f16_f32 v137, v136, v137
	v_cvt_pk_f16_f32 v136, v134, v135
	v_pk_mul_f32 v[134:135], v[130:131], v[130:131]
	global_store_dwordx2 v[92:93], v[136:137], off offset:768
	v_pk_mul_f32 v[136:137], v[132:133], v[132:133]
	v_add_f32_e32 v134, v134, v135
	v_add_f32_e32 v134, v136, v134
	v_add_f32_e32 v134, v137, v134
	s_nop 1
	v_add_f32_dpp v134, v134, v134 quad_perm:[1,0,3,2] row_mask:0xf bank_mask:0xf bound_ctrl:1
	s_nop 1
	v_add_f32_dpp v134, v134, v134 quad_perm:[2,3,0,1] row_mask:0xf bank_mask:0xf bound_ctrl:1
	s_nop 1
	v_add_f32_dpp v134, v134, v134 row_half_mirror row_mask:0xf bank_mask:0xf bound_ctrl:1
	s_nop 1
	v_add_f32_dpp v134, v134, v134 row_mirror row_mask:0xf bank_mask:0xf bound_ctrl:1
	v_mov_b32_e32 v135, v134
	s_waitcnt lgkmcnt(0)
	s_nop 1
	v_permlane16_swap_b32_e32 v134, v135
	v_add_f32_e32 v134, v134, v135
	v_fmamk_f32 v134, v134, 0x3c000000, v234
	v_cmp_gt_f32_e32 vcc, s83, v134
	v_mul_f32_e32 v135, 0x4f800000, v134
	s_nop 0
	v_cndmask_b32_e32 v134, v134, v135, vcc
	v_sqrt_f32_e32 v135, v134
	s_nop 0
	v_add_u32_e32 v136, -1, v135
	v_fma_f32 v137, -v136, v135, v134
	v_cmp_ge_f32_e64 s[44:45], 0, v137
	v_add_u32_e32 v137, 1, v135
	s_nop 0
	v_cndmask_b32_e64 v136, v135, v136, s[44:45]
	v_fma_f32 v135, -v137, v135, v134
	v_cmp_lt_f32_e64 s[44:45], 0, v135
	s_nop 1
	v_cndmask_b32_e64 v135, v136, v137, s[44:45]
	v_mul_f32_e32 v136, 0x37800000, v135
	v_cndmask_b32_e32 v135, v135, v136, vcc
	v_cmp_class_f32_e32 vcc, v134, v235
	s_nop 1
	v_cndmask_b32_e32 v134, v135, v134, vcc
	v_div_scale_f32 v135, s[2:3], v134, v134, 1.0
	v_rcp_f32_e32 v136, v135
	s_nop 0
	v_fma_f32 v137, -v135, v136, 1.0
	v_fmac_f32_e32 v136, v137, v136
	v_div_scale_f32 v137, vcc, 1.0, v134, 1.0
	v_mul_f32_e32 v138, v137, v136
	v_fma_f32 v139, -v135, v138, v137
	v_fmac_f32_e32 v138, v139, v136
	v_fma_f32 v135, -v135, v138, v137
	v_div_fmas_f32 v135, v135, v136, v138
	v_div_fixup_f32 v134, v135, v134, 1.0
	v_pk_mul_f32 v[132:133], v[132:133], v[134:135] op_sel_hi:[1,0]
	v_pk_mul_f32 v[130:131], v[130:131], v[134:135] op_sel_hi:[1,0]
	v_pk_mul_f32 v[132:133], v[6:7], v[132:133]
	v_pk_mul_f32 v[130:131], v[4:5], v[130:131]
	v_pk_mul_f32 v[132:133], v[132:133], s[36:37] op_sel_hi:[1,0]
	v_pk_mul_f32 v[130:131], v[130:131], s[36:37] op_sel_hi:[1,0]
	v_cvt_pk_f16_f32 v133, v132, v133
	v_cvt_pk_f16_f32 v132, v130, v131
	v_pk_mul_f32 v[130:131], v[126:127], v[126:127]
	global_store_dwordx2 v[92:93], v[132:133], off offset:1024
	v_pk_mul_f32 v[132:133], v[128:129], v[128:129]
	v_add_f32_e32 v130, v130, v131
	v_add_f32_e32 v130, v132, v130
	v_add_f32_e32 v130, v133, v130
	s_nop 1
	v_add_f32_dpp v130, v130, v130 quad_perm:[1,0,3,2] row_mask:0xf bank_mask:0xf bound_ctrl:1
	s_nop 1
	v_add_f32_dpp v130, v130, v130 quad_perm:[2,3,0,1] row_mask:0xf bank_mask:0xf bound_ctrl:1
	s_nop 1
	v_add_f32_dpp v130, v130, v130 row_half_mirror row_mask:0xf bank_mask:0xf bound_ctrl:1
	s_nop 1
	v_add_f32_dpp v130, v130, v130 row_mirror row_mask:0xf bank_mask:0xf bound_ctrl:1
	v_mov_b32_e32 v131, v130
	s_waitcnt lgkmcnt(0)
; __device__ __forceinline__ void phase_moba_prep(const Params& P, LAS unsigned char* lds, int l, int first, int stride) {
;     ...
;             for (int i = 0; i < 16; ++i) { const f16x4 t = raw[which][i]; v[i] = (f32x4){(float)t[0], (float)t[1], (float)t[2], (float)t[3]}; }
;             f32x4 cs = {0, 0, 0, 0};
; #pragma unroll
;             for (int i = 0; i < 16; ++i) {
;                 float ss = v[i][0] * v[i][0] + v[i][1] * v[i][1] + v[i][2] * v[i][2] + v[i][3] * v[i][3];
;                 ss = row_sum16(ss); ss += __shfl_xor(ss, 16);
;                 const float rstd = 1.0f / sqrtf(ss * (1.0f / HD) + EPS);
;                 f32x4 y = (v[i] * rstd) * gg;
;                 cs += y;
;                 if (which == 0) y = y * (0.08838834764831845f * 1.4426950408889634f);
;                 f16x4 o; o[0] = (f16)y[0]; o[1] = (f16)y[1]; o[2] = (f16)y[2]; o[3] = (f16)y[3];
;                 *(f16x4*)(dst + (size_t)i * HD) = o;
	s_nop 1
	v_permlane16_swap_b32_e32 v130, v131
	v_add_f32_e32 v130, v130, v131
	v_fmamk_f32 v130, v130, 0x3c000000, v234
	v_cmp_gt_f32_e32 vcc, s83, v130
	v_mul_f32_e32 v131, 0x4f800000, v130
	s_nop 0
	v_cndmask_b32_e32 v130, v130, v131, vcc
	v_sqrt_f32_e32 v131, v130
	s_nop 0
	v_add_u32_e32 v132, -1, v131
	v_fma_f32 v133, -v132, v131, v130
	v_cmp_ge_f32_e64 s[44:45], 0, v133
	v_add_u32_e32 v133, 1, v131
	s_nop 0
	v_cndmask_b32_e64 v132, v131, v132, s[44:45]
	v_fma_f32 v131, -v133, v131, v130
	v_cmp_lt_f32_e64 s[44:45], 0, v131
	s_nop 1
	v_cndmask_b32_e64 v131, v132, v133, s[44:45]
	v_mul_f32_e32 v132, 0x37800000, v131
	v_cndmask_b32_e32 v131, v131, v132, vcc
	v_cmp_class_f32_e32 vcc, v130, v235
	s_nop 1
	v_cndmask_b32_e32 v130, v131, v130, vcc
	v_div_scale_f32 v131, s[2:3], v130, v130, 1.0
	v_rcp_f32_e32 v132, v131
	s_nop 0
	v_fma_f32 v133, -v131, v132, 1.0
	v_fmac_f32_e32 v132, v133, v132
	v_div_scale_f32 v133, vcc, 1.0, v130, 1.0
	v_mul_f32_e32 v134, v133, v132
	v_fma_f32 v135, -v131, v134, v133
	v_fmac_f32_e32 v134, v135, v132
	v_fma_f32 v131, -v131, v134, v133
	v_div_fmas_f32 v131, v131, v132, v134
	v_div_fixup_f32 v130, v131, v130, 1.0
	v_pk_mul_f32 v[128:129], v[128:129], v[130:131] op_sel_hi:[1,0]
	v_pk_mul_f32 v[126:127], v[126:127], v[130:131] op_sel_hi:[1,0]
	v_pk_mul_f32 v[128:129], v[6:7], v[128:129]
	v_pk_mul_f32 v[126:127], v[4:5], v[126:127]
	v_pk_mul_f32 v[128:129], v[128:129], s[36:37] op_sel_hi:[1,0]
	v_pk_mul_f32 v[126:127], v[126:127], s[36:37] op_sel_hi:[1,0]
	v_cvt_pk_f16_f32 v129, v128, v129
	v_cvt_pk_f16_f32 v128, v126, v127
	v_pk_mul_f32 v[126:127], v[122:123], v[122:123]
	global_store_dwordx2 v[92:93], v[128:129], off offset:1280
	v_pk_mul_f32 v[128:129], v[124:125], v[124:125]
	v_add_f32_e32 v126, v126, v127
	v_add_f32_e32 v126, v128, v126
	v_add_f32_e32 v126, v129, v126
	s_nop 1
	v_add_f32_dpp v126, v126, v126 quad_perm:[1,0,3,2] row_mask:0xf bank_mask:0xf bound_ctrl:1
	s_nop 1
	v_add_f32_dpp v126, v126, v126 quad_perm:[2,3,0,1] row_mask:0xf bank_mask:0xf bound_ctrl:1
	s_nop 1
	v_add_f32_dpp v126, v126, v126 row_half_mirror row_mask:0xf bank_mask:0xf bound_ctrl:1
	s_nop 1
	v_add_f32_dpp v126, v126, v126 row_mirror row_mask:0xf bank_mask:0xf bound_ctrl:1
	v_mov_b32_e32 v127, v126
	s_waitcnt lgkmcnt(0)
	s_nop 1
	v_permlane16_swap_b32_e32 v126, v127
	v_add_f32_e32 v126, v126, v127
	v_fmamk_f32 v126, v126, 0x3c000000, v234
	v_cmp_gt_f32_e32 vcc, s83, v126
	v_mul_f32_e32 v127, 0x4f800000, v126
	s_nop 0
	v_cndmask_b32_e32 v126, v126, v127, vcc
	v_sqrt_f32_e32 v127, v126
	s_nop 0
	v_add_u32_e32 v128, -1, v127
	v_fma_f32 v129, -v128, v127, v126
	v_cmp_ge_f32_e64 s[44:45], 0, v129
	v_add_u32_e32 v129, 1, v127
	s_nop 0
	v_cndmask_b32_e64 v128, v127, v128, s[44:45]
	v_fma_f32 v127, -v129, v127, v126
	v_cmp_lt_f32_e64 s[44:45], 0, v127
	s_nop 1
	v_cndmask_b32_e64 v127, v128, v129, s[44:45]
	v_mul_f32_e32 v128, 0x37800000, v127
	v_cndmask_b32_e32 v127, v127, v128, vcc
	v_cmp_class_f32_e32 vcc, v126, v235
	s_nop 1
	v_cndmask_b32_e32 v126, v127, v126, vcc
	v_div_scale_f32 v127, s[2:3], v126, v126, 1.0
	v_rcp_f32_e32 v128, v127
	s_nop 0
	v_fma_f32 v129, -v127, v128, 1.0
	v_fmac_f32_e32 v128, v129, v128
	v_div_scale_f32 v129, vcc, 1.0, v126, 1.0
	v_mul_f32_e32 v130, v129, v128
	v_fma_f32 v131, -v127, v130, v129
	v_fmac_f32_e32 v130, v131, v128
	v_fma_f32 v127, -v127, v130, v129
	v_div_fmas_f32 v127, v127, v128, v130
	v_div_fixup_f32 v126, v127, v126, 1.0
	v_pk_mul_f32 v[124:125], v[124:125], v[126:127] op_sel_hi:[1,0]
	v_pk_mul_f32 v[122:123], v[122:123], v[126:127] op_sel_hi:[1,0]
	v_pk_mul_f32 v[124:125], v[6:7], v[124:125]
	v_pk_mul_f32 v[122:123], v[4:5], v[122:123]
	v_pk_mul_f32 v[124:125], v[124:125], s[36:37] op_sel_hi:[1,0]
	v_pk_mul_f32 v[122:123], v[122:123], s[36:37] op_sel_hi:[1,0]
	v_cvt_pk_f16_f32 v125, v124, v125
	v_cvt_pk_f16_f32 v124, v122, v123
	v_pk_mul_f32 v[122:123], v[118:119], v[118:119]
	global_store_dwordx2 v[92:93], v[124:125], off offset:1536
	v_pk_mul_f32 v[124:125], v[120:121], v[120:121]
	v_add_f32_e32 v122, v122, v123
	v_add_f32_e32 v122, v124, v122
	v_add_f32_e32 v122, v125, v122
	s_nop 1
	v_add_f32_dpp v122, v122, v122 quad_perm:[1,0,3,2] row_mask:0xf bank_mask:0xf bound_ctrl:1
	s_nop 1
	v_add_f32_dpp v122, v122, v122 quad_perm:[2,3,0,1] row_mask:0xf bank_mask:0xf bound_ctrl:1
	s_nop 1
	v_add_f32_dpp v122, v122, v122 row_half_mirror row_mask:0xf bank_mask:0xf bound_ctrl:1
	s_nop 1
	v_add_f32_dpp v122, v122, v122 row_mirror row_mask:0xf bank_mask:0xf bound_ctrl:1
	v_mov_b32_e32 v123, v122
	s_waitcnt lgkmcnt(0)
	s_nop 1
	v_permlane16_swap_b32_e32 v122, v123
	v_add_f32_e32 v122, v122, v123
	v_fmamk_f32 v122, v122, 0x3c000000, v234
	v_cmp_gt_f32_e32 vcc, s83, v122
	v_mul_f32_e32 v123, 0x4f800000, v122
	s_nop 0
	v_cndmask_b32_e32 v122, v122, v123, vcc
	v_sqrt_f32_e32 v123, v122
	s_nop 0
	v_add_u32_e32 v124, -1, v123
	v_fma_f32 v125, -v124, v123, v122
	v_cmp_ge_f32_e64 s[44:45], 0, v125
	v_add_u32_e32 v125, 1, v123
	s_nop 0
	v_cndmask_b32_e64 v124, v123, v124, s[44:45]
	v_fma_f32 v123, -v125, v123, v122
	v_cmp_lt_f32_e64 s[44:45], 0, v123
	s_nop 1
	v_cndmask_b32_e64 v123, v124, v125, s[44:45]
	v_mul_f32_e32 v124, 0x37800000, v123
	v_cndmask_b32_e32 v123, v123, v124, vcc
	v_cmp_class_f32_e32 vcc, v122, v235
	s_nop 1
	v_cndmask_b32_e32 v122, v123, v122, vcc
	v_div_scale_f32 v123, s[2:3], v122, v122, 1.0
	v_rcp_f32_e32 v124, v123
	s_nop 0
	v_fma_f32 v125, -v123, v124, 1.0
	v_fmac_f32_e32 v124, v125, v124
	v_div_scale_f32 v125, vcc, 1.0, v122, 1.0
	v_mul_f32_e32 v126, v125, v124
	v_fma_f32 v127, -v123, v126, v125
	v_fmac_f32_e32 v126, v127, v124
	v_fma_f32 v123, -v123, v126, v125
	v_div_fmas_f32 v123, v123, v124, v126
	v_div_fixup_f32 v122, v123, v122, 1.0
	v_pk_mul_f32 v[120:121], v[120:121], v[122:123] op_sel_hi:[1,0]
	v_pk_mul_f32 v[118:119], v[118:119], v[122:123] op_sel_hi:[1,0]
	v_pk_mul_f32 v[120:121], v[6:7], v[120:121]
	v_pk_mul_f32 v[118:119], v[4:5], v[118:119]
	v_pk_mul_f32 v[120:121], v[120:121], s[36:37] op_sel_hi:[1,0]
	v_pk_mul_f32 v[118:119], v[118:119], s[36:37] op_sel_hi:[1,0]
	v_cvt_pk_f16_f32 v121, v120, v121
	v_cvt_pk_f16_f32 v120, v118, v119
	v_pk_mul_f32 v[118:119], v[114:115], v[114:115]
	global_store_dwordx2 v[92:93], v[120:121], off offset:1792
	v_pk_mul_f32 v[120:121], v[116:117], v[116:117]
	v_add_f32_e32 v118, v118, v119
	v_add_f32_e32 v118, v120, v118
	v_add_f32_e32 v118, v121, v118
	s_waitcnt vmcnt(39)
; __device__ __forceinline__ void phase_moba_prep(const Params& P, LAS unsigned char* lds, int l, int first, int stride) {
;     ...
;             for (int i = 0; i < 16; ++i) { const f16x4 t = raw[which][i]; v[i] = (f32x4){(float)t[0], (float)t[1], (float)t[2], (float)t[3]}; }
;             f32x4 cs = {0, 0, 0, 0};
; #pragma unroll
;             for (int i = 0; i < 16; ++i) {
;                 float ss = v[i][0] * v[i][0] + v[i][1] * v[i][1] + v[i][2] * v[i][2] + v[i][3] * v[i][3];
;                 ss = row_sum16(ss); ss += __shfl_xor(ss, 16);
;                 const float rstd = 1.0f / sqrtf(ss * (1.0f / HD) + EPS);
;                 f32x4 y = (v[i] * rstd) * gg;
;                 cs += y;
;                 if (which == 0) y = y * (0.08838834764831845f * 1.4426950408889634f);
;                 f16x4 o; o[0] = (f16)y[0]; o[1] = (f16)y[1]; o[2] = (f16)y[2]; o[3] = (f16)y[3];
;                 *(f16x4*)(dst + (size_t)i * HD) = o;
	v_cvt_f32_f16_e32 v124, v70
	v_cvt_f32_f16_sdwa v125, v70 dst_sel:DWORD dst_unused:UNUSED_PAD src0_sel:WORD_1
	v_add_f32_dpp v118, v118, v118 quad_perm:[1,0,3,2] row_mask:0xf bank_mask:0xf bound_ctrl:1
	v_cvt_f32_f16_e32 v126, v71
	v_cvt_f32_f16_sdwa v127, v71 dst_sel:DWORD dst_unused:UNUSED_PAD src0_sel:WORD_1
	v_add_f32_dpp v118, v118, v118 quad_perm:[2,3,0,1] row_mask:0xf bank_mask:0xf bound_ctrl:1
	s_waitcnt vmcnt(38)
	v_cvt_f32_f16_e32 v70, v62
	v_cvt_f32_f16_sdwa v71, v62 dst_sel:DWORD dst_unused:UNUSED_PAD src0_sel:WORD_1
	v_add_f32_dpp v118, v118, v118 row_half_mirror row_mask:0xf bank_mask:0xf bound_ctrl:1
	s_nop 1
	v_add_f32_dpp v118, v118, v118 row_mirror row_mask:0xf bank_mask:0xf bound_ctrl:1
	v_mov_b32_e32 v119, v118
	s_waitcnt lgkmcnt(0)
	s_nop 1
	v_permlane16_swap_b32_e32 v118, v119
	v_add_f32_e32 v118, v118, v119
	v_fmamk_f32 v118, v118, 0x3c000000, v234
	v_cmp_gt_f32_e32 vcc, s83, v118
	v_mul_f32_e32 v119, 0x4f800000, v118
	s_nop 0
	v_cndmask_b32_e32 v118, v118, v119, vcc
	v_sqrt_f32_e32 v119, v118
	s_nop 0
	v_add_u32_e32 v120, -1, v119
	v_fma_f32 v121, -v120, v119, v118
	v_cmp_ge_f32_e64 s[44:45], 0, v121
	v_add_u32_e32 v121, 1, v119
	s_nop 0
	v_cndmask_b32_e64 v120, v119, v120, s[44:45]
	v_fma_f32 v119, -v121, v119, v118
	v_cmp_lt_f32_e64 s[44:45], 0, v119
	s_nop 1
	v_cndmask_b32_e64 v119, v120, v121, s[44:45]
	v_mul_f32_e32 v120, 0x37800000, v119
	v_cndmask_b32_e32 v119, v119, v120, vcc
	v_cmp_class_f32_e32 vcc, v118, v235
	s_nop 1
	v_cndmask_b32_e32 v118, v119, v118, vcc
	v_div_scale_f32 v119, s[2:3], v118, v118, 1.0
	v_rcp_f32_e32 v120, v119
	s_nop 0
	v_fma_f32 v121, -v119, v120, 1.0
	v_fmac_f32_e32 v120, v121, v120
	v_div_scale_f32 v121, vcc, 1.0, v118, 1.0
	v_mul_f32_e32 v122, v121, v120
	v_fma_f32 v123, -v119, v122, v121
	v_fmac_f32_e32 v122, v123, v120
	v_fma_f32 v119, -v119, v122, v121
	v_div_fmas_f32 v119, v119, v120, v122
	v_div_fixup_f32 v118, v119, v118, 1.0
	v_pk_mul_f32 v[116:117], v[116:117], v[118:119] op_sel_hi:[1,0]
	v_pk_mul_f32 v[114:115], v[114:115], v[118:119] op_sel_hi:[1,0]
	v_pk_mul_f32 v[116:117], v[6:7], v[116:117]
	v_pk_mul_f32 v[114:115], v[4:5], v[114:115]
	v_pk_mul_f32 v[116:117], v[116:117], s[36:37] op_sel_hi:[1,0]
	v_pk_mul_f32 v[114:115], v[114:115], s[36:37] op_sel_hi:[1,0]
	v_cvt_pk_f16_f32 v117, v116, v117
	v_cvt_pk_f16_f32 v116, v114, v115
	v_pk_mul_f32 v[114:115], v[110:111], v[110:111]
	global_store_dwordx2 v[92:93], v[116:117], off offset:2048
	v_pk_mul_f32 v[116:117], v[112:113], v[112:113]
	v_add_f32_e32 v114, v114, v115
	v_add_f32_e32 v114, v116, v114
	v_add_f32_e32 v114, v117, v114
	s_waitcnt vmcnt(38)
	v_cvt_f32_f16_e32 v120, v55
	v_cvt_f32_f16_sdwa v121, v55 dst_sel:DWORD dst_unused:UNUSED_PAD src0_sel:WORD_1
	v_add_f32_dpp v114, v114, v114 quad_perm:[1,0,3,2] row_mask:0xf bank_mask:0xf bound_ctrl:1
	v_cvt_f32_f16_e32 v122, v63
	v_cvt_f32_f16_sdwa v123, v63 dst_sel:DWORD dst_unused:UNUSED_PAD src0_sel:WORD_1
	v_add_f32_dpp v114, v114, v114 quad_perm:[2,3,0,1] row_mask:0xf bank_mask:0xf bound_ctrl:1
	s_nop 1
	v_add_f32_dpp v114, v114, v114 row_half_mirror row_mask:0xf bank_mask:0xf bound_ctrl:1
	s_nop 1
	v_add_f32_dpp v114, v114, v114 row_mirror row_mask:0xf bank_mask:0xf bound_ctrl:1
	v_mov_b32_e32 v115, v114
	s_waitcnt lgkmcnt(0)
	s_nop 1
	v_permlane16_swap_b32_e32 v114, v115
	v_add_f32_e32 v114, v114, v115
	v_fmamk_f32 v114, v114, 0x3c000000, v234
	v_cmp_gt_f32_e32 vcc, s83, v114
	v_mul_f32_e32 v115, 0x4f800000, v114
	s_nop 0
	v_cndmask_b32_e32 v114, v114, v115, vcc
	v_sqrt_f32_e32 v115, v114
	s_nop 0
	v_add_u32_e32 v116, -1, v115
	v_fma_f32 v117, -v116, v115, v114
	v_cmp_ge_f32_e64 s[44:45], 0, v117
	v_add_u32_e32 v117, 1, v115
	s_nop 0
	v_cndmask_b32_e64 v116, v115, v116, s[44:45]
	v_fma_f32 v115, -v117, v115, v114
	v_cmp_lt_f32_e64 s[44:45], 0, v115
	s_nop 1
	v_cndmask_b32_e64 v115, v116, v117, s[44:45]
	v_mul_f32_e32 v116, 0x37800000, v115
	v_cndmask_b32_e32 v115, v115, v116, vcc
	v_cmp_class_f32_e32 vcc, v114, v235
	s_nop 1
	v_cndmask_b32_e32 v114, v115, v114, vcc
	v_div_scale_f32 v115, s[2:3], v114, v114, 1.0
	v_rcp_f32_e32 v116, v115
	s_nop 0
	v_fma_f32 v117, -v115, v116, 1.0
	v_fmac_f32_e32 v116, v117, v116
	v_div_scale_f32 v117, vcc, 1.0, v114, 1.0
	v_mul_f32_e32 v118, v117, v116
	v_fma_f32 v119, -v115, v118, v117
	v_fmac_f32_e32 v118, v119, v116
	v_fma_f32 v115, -v115, v118, v117
	v_div_fmas_f32 v115, v115, v116, v118
	v_div_fixup_f32 v114, v115, v114, 1.0
	v_pk_mul_f32 v[112:113], v[112:113], v[114:115] op_sel_hi:[1,0]
	v_pk_mul_f32 v[110:111], v[110:111], v[114:115] op_sel_hi:[1,0]
	v_pk_mul_f32 v[112:113], v[6:7], v[112:113]
	v_pk_mul_f32 v[110:111], v[4:5], v[110:111]
	v_pk_mul_f32 v[112:113], v[112:113], s[36:37] op_sel_hi:[1,0]
	v_pk_mul_f32 v[110:111], v[110:111], s[36:37] op_sel_hi:[1,0]
	v_cvt_pk_f16_f32 v113, v112, v113
	v_cvt_pk_f16_f32 v112, v110, v111
	v_pk_mul_f32 v[110:111], v[106:107], v[106:107]
	global_store_dwordx2 v[92:93], v[112:113], off offset:2304
	v_pk_mul_f32 v[112:113], v[108:109], v[108:109]
	v_add_f32_e32 v110, v110, v111
	v_add_f32_e32 v110, v112, v110
	v_add_f32_e32 v110, v113, v110
	v_cvt_f32_f16_e32 v118, v54
	v_cvt_f32_f16_sdwa v119, v54 dst_sel:DWORD dst_unused:UNUSED_PAD src0_sel:WORD_1
	v_add_f32_dpp v110, v110, v110 quad_perm:[1,0,3,2] row_mask:0xf bank_mask:0xf bound_ctrl:1
	v_pk_mul_f32 v[54:55], v[124:125], v[124:125]
	s_waitcnt vmcnt(38)
	v_cvt_f32_f16_e32 v116, v53
	v_add_f32_dpp v110, v110, v110 quad_perm:[2,3,0,1] row_mask:0xf bank_mask:0xf bound_ctrl:1
	v_cvt_f32_f16_sdwa v117, v53 dst_sel:DWORD dst_unused:UNUSED_PAD src0_sel:WORD_1
	s_waitcnt vmcnt(26)
; __device__ __forceinline__ void phase_moba_prep(const Params& P, LAS unsigned char* lds, int l, int first, int stride) {
;     ...
;             for (int i = 0; i < 16; ++i) { const f16x4 t = raw[which][i]; v[i] = (f32x4){(float)t[0], (float)t[1], (float)t[2], (float)t[3]}; }
;             f32x4 cs = {0, 0, 0, 0};
; #pragma unroll
;             for (int i = 0; i < 16; ++i) {
;                 float ss = v[i][0] * v[i][0] + v[i][1] * v[i][1] + v[i][2] * v[i][2] + v[i][3] * v[i][3];
;                 ss = row_sum16(ss); ss += __shfl_xor(ss, 16);
;                 const float rstd = 1.0f / sqrtf(ss * (1.0f / HD) + EPS);
;                 f32x4 y = (v[i] * rstd) * gg;
;                 cs += y;
;                 if (which == 0) y = y * (0.08838834764831845f * 1.4426950408889634f);
;                 f16x4 o; o[0] = (f16)y[0]; o[1] = (f16)y[1]; o[2] = (f16)y[2]; o[3] = (f16)y[3];
;                 *(f16x4*)(dst + (size_t)i * HD) = o;
	v_cvt_f32_f16_sdwa v53, v57 dst_sel:DWORD dst_unused:UNUSED_PAD src0_sel:WORD_1
	v_add_f32_dpp v110, v110, v110 row_half_mirror row_mask:0xf bank_mask:0xf bound_ctrl:1
	v_add_f32_e32 v54, v54, v55
	s_nop 0
	v_add_f32_dpp v110, v110, v110 row_mirror row_mask:0xf bank_mask:0xf bound_ctrl:1
	v_mov_b32_e32 v111, v110
	s_waitcnt lgkmcnt(0)
	s_nop 1
	v_permlane16_swap_b32_e32 v110, v111
	v_add_f32_e32 v110, v110, v111
	v_fmamk_f32 v110, v110, 0x3c000000, v234
	v_cmp_gt_f32_e32 vcc, s83, v110
	v_mul_f32_e32 v111, 0x4f800000, v110
	s_nop 0
	v_cndmask_b32_e32 v110, v110, v111, vcc
	v_sqrt_f32_e32 v111, v110
	s_nop 0
	v_add_u32_e32 v112, -1, v111
	v_fma_f32 v113, -v112, v111, v110
	v_cmp_ge_f32_e64 s[44:45], 0, v113
	v_add_u32_e32 v113, 1, v111
	s_nop 0
	v_cndmask_b32_e64 v112, v111, v112, s[44:45]
	v_fma_f32 v111, -v113, v111, v110
	v_cmp_lt_f32_e64 s[44:45], 0, v111
	s_nop 1
	v_cndmask_b32_e64 v111, v112, v113, s[44:45]
	v_mul_f32_e32 v112, 0x37800000, v111
	v_cndmask_b32_e32 v111, v111, v112, vcc
	v_cmp_class_f32_e32 vcc, v110, v235
	s_nop 1
	v_cndmask_b32_e32 v110, v111, v110, vcc
	v_div_scale_f32 v111, s[2:3], v110, v110, 1.0
	v_rcp_f32_e32 v112, v111
	s_nop 0
	v_fma_f32 v113, -v111, v112, 1.0
	v_fmac_f32_e32 v112, v113, v112
	v_div_scale_f32 v113, vcc, 1.0, v110, 1.0
	v_mul_f32_e32 v114, v113, v112
	v_fma_f32 v115, -v111, v114, v113
	v_fmac_f32_e32 v114, v115, v112
	v_fma_f32 v111, -v111, v114, v113
	v_div_fmas_f32 v111, v111, v112, v114
	v_div_fixup_f32 v110, v111, v110, 1.0
	v_pk_mul_f32 v[108:109], v[108:109], v[110:111] op_sel_hi:[1,0]
	v_pk_mul_f32 v[106:107], v[106:107], v[110:111] op_sel_hi:[1,0]
	v_pk_mul_f32 v[108:109], v[6:7], v[108:109]
	v_pk_mul_f32 v[106:107], v[4:5], v[106:107]
	v_pk_mul_f32 v[108:109], v[108:109], s[36:37] op_sel_hi:[1,0]
	v_pk_mul_f32 v[106:107], v[106:107], s[36:37] op_sel_hi:[1,0]
	v_cvt_pk_f16_f32 v109, v108, v109
	v_cvt_pk_f16_f32 v108, v106, v107
	v_pk_mul_f32 v[106:107], v[102:103], v[102:103]
	global_store_dwordx2 v[92:93], v[108:109], off offset:2560
	v_pk_mul_f32 v[108:109], v[104:105], v[104:105]
	v_add_f32_e32 v106, v106, v107
	v_add_f32_e32 v106, v108, v106
	v_add_f32_e32 v106, v109, v106
	v_cvt_f32_f16_e32 v112, v80
	v_cvt_f32_f16_sdwa v113, v80 dst_sel:DWORD dst_unused:UNUSED_PAD src0_sel:WORD_1
	v_add_f32_dpp v106, v106, v106 quad_perm:[1,0,3,2] row_mask:0xf bank_mask:0xf bound_ctrl:1
	v_cvt_f32_f16_e32 v114, v81
	v_cvt_f32_f16_sdwa v115, v81 dst_sel:DWORD dst_unused:UNUSED_PAD src0_sel:WORD_1
	v_add_f32_dpp v106, v106, v106 quad_perm:[2,3,0,1] row_mask:0xf bank_mask:0xf bound_ctrl:1
	v_cvt_f32_f16_e32 v80, v58
	v_cvt_f32_f16_sdwa v81, v58 dst_sel:DWORD dst_unused:UNUSED_PAD src0_sel:WORD_1
	v_add_f32_dpp v106, v106, v106 row_half_mirror row_mask:0xf bank_mask:0xf bound_ctrl:1
	v_cvt_f32_f16_e32 v58, v60
	s_nop 0
	v_add_f32_dpp v106, v106, v106 row_mirror row_mask:0xf bank_mask:0xf bound_ctrl:1
	v_mov_b32_e32 v107, v106
	s_waitcnt lgkmcnt(0)
	s_nop 1
	v_permlane16_swap_b32_e32 v106, v107
	v_add_f32_e32 v106, v106, v107
	v_fmamk_f32 v106, v106, 0x3c000000, v234
	v_cmp_gt_f32_e32 vcc, s83, v106
	v_mul_f32_e32 v107, 0x4f800000, v106
	s_nop 0
	v_cndmask_b32_e32 v106, v106, v107, vcc
	v_sqrt_f32_e32 v107, v106
	s_nop 0
	v_add_u32_e32 v108, -1, v107
	v_fma_f32 v109, -v108, v107, v106
	v_cmp_ge_f32_e64 s[44:45], 0, v109
	v_add_u32_e32 v109, 1, v107
	s_nop 0
	v_cndmask_b32_e64 v108, v107, v108, s[44:45]
	v_fma_f32 v107, -v109, v107, v106
	v_cmp_lt_f32_e64 s[44:45], 0, v107
	s_nop 1
	v_cndmask_b32_e64 v107, v108, v109, s[44:45]
	v_mul_f32_e32 v108, 0x37800000, v107
	v_cndmask_b32_e32 v107, v107, v108, vcc
	v_cmp_class_f32_e32 vcc, v106, v235
	s_nop 1
	v_cndmask_b32_e32 v106, v107, v106, vcc
	v_div_scale_f32 v107, s[2:3], v106, v106, 1.0
	v_rcp_f32_e32 v108, v107
	s_nop 0
	v_fma_f32 v109, -v107, v108, 1.0
	v_fmac_f32_e32 v108, v109, v108
	v_div_scale_f32 v109, vcc, 1.0, v106, 1.0
	v_mul_f32_e32 v110, v109, v108
	v_fma_f32 v111, -v107, v110, v109
	v_fmac_f32_e32 v110, v111, v108
	v_fma_f32 v107, -v107, v110, v109
	v_div_fmas_f32 v107, v107, v108, v110
	v_div_fixup_f32 v106, v107, v106, 1.0
	v_pk_mul_f32 v[104:105], v[104:105], v[106:107] op_sel_hi:[1,0]
	v_pk_mul_f32 v[102:103], v[102:103], v[106:107] op_sel_hi:[1,0]
	v_pk_mul_f32 v[104:105], v[6:7], v[104:105]
	v_pk_mul_f32 v[102:103], v[4:5], v[102:103]
	v_pk_mul_f32 v[104:105], v[104:105], s[36:37] op_sel_hi:[1,0]
	v_pk_mul_f32 v[102:103], v[102:103], s[36:37] op_sel_hi:[1,0]
	v_cvt_pk_f16_f32 v105, v104, v105
	v_cvt_pk_f16_f32 v104, v102, v103
	v_pk_mul_f32 v[102:103], v[98:99], v[98:99]
	global_store_dwordx2 v[92:93], v[104:105], off offset:2816
	v_pk_mul_f32 v[104:105], v[100:101], v[100:101]
	v_add_f32_e32 v102, v102, v103
	v_add_f32_e32 v102, v104, v102
	v_add_f32_e32 v102, v105, v102
	v_cvt_f32_f16_e32 v108, v66
	v_cvt_f32_f16_sdwa v109, v66 dst_sel:DWORD dst_unused:UNUSED_PAD src0_sel:WORD_1
	v_add_f32_dpp v102, v102, v102 quad_perm:[1,0,3,2] row_mask:0xf bank_mask:0xf bound_ctrl:1
	v_cvt_f32_f16_e32 v110, v67
	v_cvt_f32_f16_sdwa v111, v67 dst_sel:DWORD dst_unused:UNUSED_PAD src0_sel:WORD_1
	v_add_f32_dpp v102, v102, v102 quad_perm:[2,3,0,1] row_mask:0xf bank_mask:0xf bound_ctrl:1
	v_cvt_f32_f16_e32 v66, v64
	v_cvt_f32_f16_sdwa v67, v64 dst_sel:DWORD dst_unused:UNUSED_PAD src0_sel:WORD_1
	v_add_f32_dpp v102, v102, v102 row_half_mirror row_mask:0xf bank_mask:0xf bound_ctrl:1
	v_cvt_f32_f16_e32 v64, v65
	v_cvt_f32_f16_sdwa v65, v65 dst_sel:DWORD dst_unused:UNUSED_PAD src0_sel:WORD_1
	v_add_f32_dpp v102, v102, v102 row_mirror row_mask:0xf bank_mask:0xf bound_ctrl:1
	v_mov_b32_e32 v103, v102
	s_waitcnt lgkmcnt(0)
; __device__ __forceinline__ void phase_moba_prep(const Params& P, LAS unsigned char* lds, int l, int first, int stride) {
;     ...
;             for (int i = 0; i < 16; ++i) { const f16x4 t = raw[which][i]; v[i] = (f32x4){(float)t[0], (float)t[1], (float)t[2], (float)t[3]}; }
;             f32x4 cs = {0, 0, 0, 0};
; #pragma unroll
;             for (int i = 0; i < 16; ++i) {
;                 float ss = v[i][0] * v[i][0] + v[i][1] * v[i][1] + v[i][2] * v[i][2] + v[i][3] * v[i][3];
;                 ss = row_sum16(ss); ss += __shfl_xor(ss, 16);
;                 const float rstd = 1.0f / sqrtf(ss * (1.0f / HD) + EPS);
;                 f32x4 y = (v[i] * rstd) * gg;
;                 cs += y;
;                 if (which == 0) y = y * (0.08838834764831845f * 1.4426950408889634f);
;                 f16x4 o; o[0] = (f16)y[0]; o[1] = (f16)y[1]; o[2] = (f16)y[2]; o[3] = (f16)y[3];
;                 *(f16x4*)(dst + (size_t)i * HD) = o;
	s_nop 1
	v_permlane16_swap_b32_e32 v102, v103
	v_add_f32_e32 v102, v102, v103
	v_fmamk_f32 v102, v102, 0x3c000000, v234
	v_cmp_gt_f32_e32 vcc, s83, v102
	v_mul_f32_e32 v103, 0x4f800000, v102
	s_nop 0
	v_cndmask_b32_e32 v102, v102, v103, vcc
	v_sqrt_f32_e32 v103, v102
	s_nop 0
	v_add_u32_e32 v104, -1, v103
	v_fma_f32 v105, -v104, v103, v102
	v_cmp_ge_f32_e64 s[44:45], 0, v105
	v_add_u32_e32 v105, 1, v103
	s_nop 0
	v_cndmask_b32_e64 v104, v103, v104, s[44:45]
	v_fma_f32 v103, -v105, v103, v102
	v_cmp_lt_f32_e64 s[44:45], 0, v103
	s_nop 1
	v_cndmask_b32_e64 v103, v104, v105, s[44:45]
	v_mul_f32_e32 v104, 0x37800000, v103
	v_cndmask_b32_e32 v103, v103, v104, vcc
	v_cmp_class_f32_e32 vcc, v102, v235
	s_nop 1
	v_cndmask_b32_e32 v102, v103, v102, vcc
	v_div_scale_f32 v103, s[2:3], v102, v102, 1.0
	v_rcp_f32_e32 v104, v103
	s_nop 0
	v_fma_f32 v105, -v103, v104, 1.0
	v_fmac_f32_e32 v104, v105, v104
	v_div_scale_f32 v105, vcc, 1.0, v102, 1.0
	v_mul_f32_e32 v106, v105, v104
	v_fma_f32 v107, -v103, v106, v105
	v_fmac_f32_e32 v106, v107, v104
	v_fma_f32 v103, -v103, v106, v105
	v_div_fmas_f32 v103, v103, v104, v106
	v_div_fixup_f32 v102, v103, v102, 1.0
	v_pk_mul_f32 v[100:101], v[100:101], v[102:103] op_sel_hi:[1,0]
	v_pk_mul_f32 v[98:99], v[98:99], v[102:103] op_sel_hi:[1,0]
	v_pk_mul_f32 v[100:101], v[6:7], v[100:101]
	v_pk_mul_f32 v[98:99], v[4:5], v[98:99]
	v_pk_mul_f32 v[100:101], v[100:101], s[36:37] op_sel_hi:[1,0]
	v_pk_mul_f32 v[98:99], v[98:99], s[36:37] op_sel_hi:[1,0]
	v_cvt_pk_f16_f32 v101, v100, v101
	v_cvt_pk_f16_f32 v100, v98, v99
	v_pk_mul_f32 v[98:99], v[94:95], v[94:95]
	global_store_dwordx2 v[92:93], v[100:101], off offset:3072
	v_pk_mul_f32 v[100:101], v[96:97], v[96:97]
	v_add_f32_e32 v98, v98, v99
	v_add_f32_e32 v98, v100, v98
	v_add_f32_e32 v98, v101, v98
	v_cvt_f32_f16_e32 v104, v78
	v_cvt_f32_f16_sdwa v105, v78 dst_sel:DWORD dst_unused:UNUSED_PAD src0_sel:WORD_1
	v_add_f32_dpp v98, v98, v98 quad_perm:[1,0,3,2] row_mask:0xf bank_mask:0xf bound_ctrl:1
	v_cvt_f32_f16_e32 v106, v79
	v_cvt_f32_f16_sdwa v107, v79 dst_sel:DWORD dst_unused:UNUSED_PAD src0_sel:WORD_1
	v_add_f32_dpp v98, v98, v98 quad_perm:[2,3,0,1] row_mask:0xf bank_mask:0xf bound_ctrl:1
	s_nop 1
	v_add_f32_dpp v98, v98, v98 row_half_mirror row_mask:0xf bank_mask:0xf bound_ctrl:1
	s_nop 1
	v_add_f32_dpp v98, v98, v98 row_mirror row_mask:0xf bank_mask:0xf bound_ctrl:1
	v_mov_b32_e32 v99, v98
	s_waitcnt lgkmcnt(0)
	s_nop 1
	v_permlane16_swap_b32_e32 v98, v99
	v_add_f32_e32 v98, v98, v99
	v_fmamk_f32 v98, v98, 0x3c000000, v234
	v_cmp_gt_f32_e32 vcc, s83, v98
	v_mul_f32_e32 v99, 0x4f800000, v98
	s_nop 0
	v_cndmask_b32_e32 v98, v98, v99, vcc
	v_sqrt_f32_e32 v99, v98
	s_nop 0
	v_add_u32_e32 v100, -1, v99
	v_fma_f32 v101, -v100, v99, v98
	v_cmp_ge_f32_e64 s[44:45], 0, v101
	v_add_u32_e32 v101, 1, v99
	s_nop 0
	v_cndmask_b32_e64 v100, v99, v100, s[44:45]
	v_fma_f32 v99, -v101, v99, v98
	v_cmp_lt_f32_e64 s[44:45], 0, v99
	s_nop 1
	v_cndmask_b32_e64 v99, v100, v101, s[44:45]
	v_mul_f32_e32 v100, 0x37800000, v99
	v_cndmask_b32_e32 v99, v99, v100, vcc
	v_cmp_class_f32_e32 vcc, v98, v235
	s_nop 1
	v_cndmask_b32_e32 v98, v99, v98, vcc
	v_div_scale_f32 v99, s[2:3], v98, v98, 1.0
	v_rcp_f32_e32 v100, v99
	s_nop 0
	v_fma_f32 v101, -v99, v100, 1.0
	v_fmac_f32_e32 v100, v101, v100
	v_div_scale_f32 v101, vcc, 1.0, v98, 1.0
	v_mul_f32_e32 v102, v101, v100
	v_fma_f32 v103, -v99, v102, v101
	v_fmac_f32_e32 v102, v103, v100
	v_fma_f32 v99, -v99, v102, v101
	v_div_fmas_f32 v99, v99, v100, v102
	v_div_fixup_f32 v98, v99, v98, 1.0
	v_pk_mul_f32 v[96:97], v[96:97], v[98:99] op_sel_hi:[1,0]
	v_pk_mul_f32 v[94:95], v[94:95], v[98:99] op_sel_hi:[1,0]
	v_pk_mul_f32 v[96:97], v[6:7], v[96:97]
	v_pk_mul_f32 v[94:95], v[4:5], v[94:95]
	v_pk_mul_f32 v[96:97], v[96:97], s[36:37] op_sel_hi:[1,0]
	v_pk_mul_f32 v[94:95], v[94:95], s[36:37] op_sel_hi:[1,0]
	v_cvt_pk_f16_f32 v97, v96, v97
	v_cvt_pk_f16_f32 v96, v94, v95
	v_pk_mul_f32 v[94:95], v[88:89], v[88:89]
	global_store_dwordx2 v[92:93], v[96:97], off offset:3328
	v_pk_mul_f32 v[96:97], v[90:91], v[90:91]
	v_add_f32_e32 v94, v94, v95
	v_add_f32_e32 v94, v96, v94
	v_add_f32_e32 v94, v97, v94
	v_cvt_f32_f16_e32 v100, v74
	v_cvt_f32_f16_sdwa v101, v74 dst_sel:DWORD dst_unused:UNUSED_PAD src0_sel:WORD_1
	v_add_f32_dpp v94, v94, v94 quad_perm:[1,0,3,2] row_mask:0xf bank_mask:0xf bound_ctrl:1
	v_cvt_f32_f16_e32 v102, v75
	v_cvt_f32_f16_sdwa v103, v75 dst_sel:DWORD dst_unused:UNUSED_PAD src0_sel:WORD_1
	v_add_f32_dpp v94, v94, v94 quad_perm:[2,3,0,1] row_mask:0xf bank_mask:0xf bound_ctrl:1
	v_cvt_f32_f16_e32 v74, v72
	v_cvt_f32_f16_sdwa v75, v72 dst_sel:DWORD dst_unused:UNUSED_PAD src0_sel:WORD_1
	v_add_f32_dpp v94, v94, v94 row_half_mirror row_mask:0xf bank_mask:0xf bound_ctrl:1
	v_cvt_f32_f16_e32 v72, v73
	v_cvt_f32_f16_sdwa v73, v73 dst_sel:DWORD dst_unused:UNUSED_PAD src0_sel:WORD_1
	v_add_f32_dpp v94, v94, v94 row_mirror row_mask:0xf bank_mask:0xf bound_ctrl:1
	v_mov_b32_e32 v95, v94
	s_waitcnt lgkmcnt(0)
; __device__ __forceinline__ void phase_moba_prep(const Params& P, LAS unsigned char* lds, int l, int first, int stride) {
;     ...
;             for (int i = 0; i < 16; ++i) { const f16x4 t = raw[which][i]; v[i] = (f32x4){(float)t[0], (float)t[1], (float)t[2], (float)t[3]}; }
;             f32x4 cs = {0, 0, 0, 0};
; #pragma unroll
;             for (int i = 0; i < 16; ++i) {
;                 float ss = v[i][0] * v[i][0] + v[i][1] * v[i][1] + v[i][2] * v[i][2] + v[i][3] * v[i][3];
;                 ss = row_sum16(ss); ss += __shfl_xor(ss, 16);
;                 const float rstd = 1.0f / sqrtf(ss * (1.0f / HD) + EPS);
;                 f32x4 y = (v[i] * rstd) * gg;
;                 cs += y;
;                 if (which == 0) y = y * (0.08838834764831845f * 1.4426950408889634f);
;                 f16x4 o; o[0] = (f16)y[0]; o[1] = (f16)y[1]; o[2] = (f16)y[2]; o[3] = (f16)y[3];
;                 *(f16x4*)(dst + (size_t)i * HD) = o;
	s_nop 1
	v_permlane16_swap_b32_e32 v94, v95
	v_add_f32_e32 v94, v94, v95
	v_fmamk_f32 v94, v94, 0x3c000000, v234
	v_cmp_gt_f32_e32 vcc, s83, v94
	v_mul_f32_e32 v95, 0x4f800000, v94
	s_nop 0
	v_cndmask_b32_e32 v94, v94, v95, vcc
	v_sqrt_f32_e32 v95, v94
	s_nop 0
	v_add_u32_e32 v96, -1, v95
	v_fma_f32 v97, -v96, v95, v94
	v_cmp_ge_f32_e64 s[44:45], 0, v97
	v_add_u32_e32 v97, 1, v95
	s_nop 0
	v_cndmask_b32_e64 v96, v95, v96, s[44:45]
	v_fma_f32 v95, -v97, v95, v94
	v_cmp_lt_f32_e64 s[44:45], 0, v95
	s_nop 1
	v_cndmask_b32_e64 v95, v96, v97, s[44:45]
	v_mul_f32_e32 v96, 0x37800000, v95
	v_cndmask_b32_e32 v95, v95, v96, vcc
	v_cmp_class_f32_e32 vcc, v94, v235
	s_nop 1
	v_cndmask_b32_e32 v94, v95, v94, vcc
	v_div_scale_f32 v95, s[2:3], v94, v94, 1.0
	v_rcp_f32_e32 v96, v95
	s_nop 0
	v_fma_f32 v97, -v95, v96, 1.0
	v_fmac_f32_e32 v96, v97, v96
	v_div_scale_f32 v97, vcc, 1.0, v94, 1.0
	v_mul_f32_e32 v98, v97, v96
	v_fma_f32 v99, -v95, v98, v97
	v_fmac_f32_e32 v98, v99, v96
	v_fma_f32 v95, -v95, v98, v97
	v_div_fmas_f32 v95, v95, v96, v98
	v_div_fixup_f32 v94, v95, v94, 1.0
	v_pk_mul_f32 v[90:91], v[90:91], v[94:95] op_sel_hi:[1,0]
	v_pk_mul_f32 v[88:89], v[88:89], v[94:95] op_sel_hi:[1,0]
	v_pk_mul_f32 v[90:91], v[6:7], v[90:91]
	v_pk_mul_f32 v[88:89], v[4:5], v[88:89]
	v_pk_mul_f32 v[90:91], v[90:91], s[36:37] op_sel_hi:[1,0]
	v_pk_mul_f32 v[88:89], v[88:89], s[36:37] op_sel_hi:[1,0]
	v_cvt_pk_f16_f32 v91, v90, v91
	v_cvt_pk_f16_f32 v90, v88, v89
	v_pk_mul_f32 v[88:89], v[84:85], v[84:85]
	global_store_dwordx2 v[92:93], v[90:91], off offset:3584
	v_pk_mul_f32 v[90:91], v[86:87], v[86:87]
	v_add_f32_e32 v88, v88, v89
	v_add_f32_e32 v88, v90, v88
	v_add_f32_e32 v88, v91, v88
	v_cvt_f32_f16_e32 v98, v77
	v_cvt_f32_f16_sdwa v99, v77 dst_sel:DWORD dst_unused:UNUSED_PAD src0_sel:WORD_1
	v_add_f32_dpp v88, v88, v88 quad_perm:[1,0,3,2] row_mask:0xf bank_mask:0xf bound_ctrl:1
	v_cvt_f32_f16_e32 v96, v76
	v_cvt_f32_f16_sdwa v97, v76 dst_sel:DWORD dst_unused:UNUSED_PAD src0_sel:WORD_1
	v_add_f32_dpp v88, v88, v88 quad_perm:[2,3,0,1] row_mask:0xf bank_mask:0xf bound_ctrl:1
	s_nop 1
	v_add_f32_dpp v88, v88, v88 row_half_mirror row_mask:0xf bank_mask:0xf bound_ctrl:1
	s_nop 1
	v_add_f32_dpp v88, v88, v88 row_mirror row_mask:0xf bank_mask:0xf bound_ctrl:1
	v_mov_b32_e32 v89, v88
	s_waitcnt lgkmcnt(0)
	s_nop 1
	v_permlane16_swap_b32_e32 v88, v89
	v_add_f32_e32 v88, v88, v89
	v_fmamk_f32 v88, v88, 0x3c000000, v234
	v_cmp_gt_f32_e32 vcc, s83, v88
	v_mul_f32_e32 v89, 0x4f800000, v88
	s_nop 0
	v_cndmask_b32_e32 v88, v88, v89, vcc
	v_sqrt_f32_e32 v89, v88
	s_nop 0
	v_add_u32_e32 v90, -1, v89
	v_fma_f32 v91, -v90, v89, v88
	v_cmp_ge_f32_e64 s[44:45], 0, v91
	v_add_u32_e32 v91, 1, v89
	s_nop 0
	v_cndmask_b32_e64 v90, v89, v90, s[44:45]
	v_fma_f32 v89, -v91, v89, v88
	v_cmp_lt_f32_e64 s[44:45], 0, v89
	s_nop 1
	v_cndmask_b32_e64 v89, v90, v91, s[44:45]
	v_mul_f32_e32 v90, 0x37800000, v89
	v_cndmask_b32_e32 v89, v89, v90, vcc
	v_cmp_class_f32_e32 vcc, v88, v235
	s_nop 1
	v_cndmask_b32_e32 v88, v89, v88, vcc
	v_div_scale_f32 v89, s[2:3], v88, v88, 1.0
	v_rcp_f32_e32 v90, v89
	s_nop 0
	v_fma_f32 v91, -v89, v90, 1.0
	v_fmac_f32_e32 v90, v91, v90
	v_div_scale_f32 v91, vcc, 1.0, v88, 1.0
	v_mul_f32_e32 v94, v91, v90
	v_fma_f32 v95, -v89, v94, v91
	v_fmac_f32_e32 v94, v95, v90
	v_fma_f32 v89, -v89, v94, v91
	v_div_fmas_f32 v89, v89, v90, v94
	v_div_fixup_f32 v88, v89, v88, 1.0
	v_pk_mul_f32 v[86:87], v[86:87], v[88:89] op_sel_hi:[1,0]
	v_pk_mul_f32 v[84:85], v[84:85], v[88:89] op_sel_hi:[1,0]
	v_pk_mul_f32 v[86:87], v[6:7], v[86:87]
	v_pk_mul_f32 v[84:85], v[4:5], v[84:85]
	v_pk_mul_f32 v[86:87], v[86:87], s[36:37] op_sel_hi:[1,0]
	v_pk_mul_f32 v[84:85], v[84:85], s[36:37] op_sel_hi:[1,0]
	v_cvt_pk_f16_f32 v87, v86, v87
	v_cvt_pk_f16_f32 v86, v84, v85
	global_store_dwordx2 v[92:93], v[86:87], off offset:3840
	v_cvt_f32_f16_e32 v86, v52
	v_cvt_f32_f16_sdwa v87, v52 dst_sel:DWORD dst_unused:UNUSED_PAD src0_sel:WORD_1
	v_cvt_f32_f16_e32 v92, v50
	v_cvt_f32_f16_sdwa v93, v50 dst_sel:DWORD dst_unused:UNUSED_PAD src0_sel:WORD_1
	v_cvt_f32_f16_e32 v94, v51
	v_cvt_f32_f16_sdwa v95, v51 dst_sel:DWORD dst_unused:UNUSED_PAD src0_sel:WORD_1
	v_cvt_f32_f16_e32 v50, v56
	v_cvt_f32_f16_sdwa v51, v56 dst_sel:DWORD dst_unused:UNUSED_PAD src0_sel:WORD_1
	v_cvt_f32_f16_e32 v52, v57
	v_pk_mul_f32 v[56:57], v[126:127], v[126:127]
	v_cvt_f32_f16_e32 v88, v68
	v_add_f32_e32 v54, v56, v54
	v_add_f32_e32 v54, v57, v54
	v_cvt_f32_f16_sdwa v89, v68 dst_sel:DWORD dst_unused:UNUSED_PAD src0_sel:WORD_1
	v_cvt_f32_f16_e32 v90, v69
	v_add_f32_dpp v54, v54, v54 quad_perm:[1,0,3,2] row_mask:0xf bank_mask:0xf bound_ctrl:1
	v_cvt_f32_f16_sdwa v91, v69 dst_sel:DWORD dst_unused:UNUSED_PAD src0_sel:WORD_1
	v_cvt_f32_f16_e32 v84, v59
	v_add_f32_dpp v54, v54, v54 quad_perm:[2,3,0,1] row_mask:0xf bank_mask:0xf bound_ctrl:1
	v_cvt_f32_f16_sdwa v85, v59 dst_sel:DWORD dst_unused:UNUSED_PAD src0_sel:WORD_1
	v_cvt_f32_f16_sdwa v59, v60 dst_sel:DWORD dst_unused:UNUSED_PAD src0_sel:WORD_1
	v_add_f32_dpp v54, v54, v54 row_half_mirror row_mask:0xf bank_mask:0xf bound_ctrl:1
	v_cvt_f32_f16_e32 v60, v61
	v_cvt_f32_f16_sdwa v61, v61 dst_sel:DWORD dst_unused:UNUSED_PAD src0_sel:WORD_1
	v_add_f32_dpp v54, v54, v54 row_mirror row_mask:0xf bank_mask:0xf bound_ctrl:1
	v_mov_b32_e32 v55, v54
	s_waitcnt lgkmcnt(0)
; __device__ __forceinline__ void phase_moba_prep(const Params& P, LAS unsigned char* lds, int l, int first, int stride) {
;     ...
;             for (int i = 0; i < 16; ++i) { const f16x4 t = raw[which][i]; v[i] = (f32x4){(float)t[0], (float)t[1], (float)t[2], (float)t[3]}; }
;             f32x4 cs = {0, 0, 0, 0};
; #pragma unroll
;             for (int i = 0; i < 16; ++i) {
;                 float ss = v[i][0] * v[i][0] + v[i][1] * v[i][1] + v[i][2] * v[i][2] + v[i][3] * v[i][3];
;                 ss = row_sum16(ss); ss += __shfl_xor(ss, 16);
;                 const float rstd = 1.0f / sqrtf(ss * (1.0f / HD) + EPS);
;                 f32x4 y = (v[i] * rstd) * gg;
;                 cs += y;
;                 if (which == 0) y = y * (0.08838834764831845f * 1.4426950408889634f);
;                 f16x4 o; o[0] = (f16)y[0]; o[1] = (f16)y[1]; o[2] = (f16)y[2]; o[3] = (f16)y[3];
;                 *(f16x4*)(dst + (size_t)i * HD) = o;
;             }
	s_nop 1
	v_permlane16_swap_b32_e32 v54, v55
	v_add_f32_e32 v54, v54, v55
	v_fmamk_f32 v54, v54, 0x3c000000, v234
	v_cmp_gt_f32_e32 vcc, s83, v54
	v_mul_f32_e32 v55, 0x4f800000, v54
	s_nop 0
	v_cndmask_b32_e32 v54, v54, v55, vcc
	v_sqrt_f32_e32 v55, v54
	s_nop 0
	v_add_u32_e32 v56, -1, v55
	v_fma_f32 v57, -v56, v55, v54
	v_cmp_ge_f32_e64 s[44:45], 0, v57
	v_add_u32_e32 v57, 1, v55
	s_nop 0
	v_cndmask_b32_e64 v56, v55, v56, s[44:45]
	v_fma_f32 v55, -v57, v55, v54
	v_cmp_lt_f32_e64 s[44:45], 0, v55
	s_nop 1
	v_cndmask_b32_e64 v55, v56, v57, s[44:45]
	v_mul_f32_e32 v56, 0x37800000, v55
	v_cndmask_b32_e32 v55, v55, v56, vcc
	v_cmp_class_f32_e32 vcc, v54, v235
	s_nop 1
	v_cndmask_b32_e32 v54, v55, v54, vcc
	v_div_scale_f32 v55, s[2:3], v54, v54, 1.0
	v_rcp_f32_e32 v56, v55
	s_mov_b32 s2, 0x3eff1000
	v_fma_f32 v57, -v55, v56, 1.0
	v_fmac_f32_e32 v56, v57, v56
	v_div_scale_f32 v57, vcc, 1.0, v54, 1.0
	v_mul_f32_e32 v62, v57, v56
	v_fma_f32 v63, -v55, v62, v57
	v_fmac_f32_e32 v62, v63, v56
	v_fma_f32 v55, -v55, v62, v57
	v_div_fmas_f32 v55, v55, v56, v62
	v_div_fixup_f32 v56, v55, v54, 1.0
	v_pk_mul_f32 v[54:55], v[124:125], v[56:57] op_sel_hi:[1,0]
	v_pk_mul_f32 v[56:57], v[126:127], v[56:57] op_sel_hi:[1,0]
	v_pk_mul_f32 v[68:69], v[8:9], v[54:55]
	v_pk_mul_f32 v[62:63], v[10:11], v[56:57]
	v_cvt_pk_f16_f32 v76, v68, v69
	v_cvt_pk_f16_f32 v77, v62, v63
	v_add_co_u32_e32 v62, vcc, s2, v82
	v_pk_mul_f32 v[68:69], v[70:71], v[70:71]
	s_nop 0
	v_addc_co_u32_e32 v63, vcc, 0, v83, vcc
	global_store_dwordx2 v[62:63], v[76:77], off
	v_pk_mul_f32 v[76:77], v[122:123], v[122:123]
	v_add_f32_e32 v68, v68, v69
	v_add_f32_e32 v68, v76, v68
	v_add_f32_e32 v68, v77, v68
	v_pk_fma_f32 v[54:55], v[8:9], v[54:55], 0 op_sel_hi:[1,1,0]
	v_pk_fma_f32 v[56:57], v[10:11], v[56:57], 0 op_sel_hi:[1,1,0]
	v_add_f32_dpp v68, v68, v68 quad_perm:[1,0,3,2] row_mask:0xf bank_mask:0xf bound_ctrl:1
	s_nop 1
	v_add_f32_dpp v68, v68, v68 quad_perm:[2,3,0,1] row_mask:0xf bank_mask:0xf bound_ctrl:1
	s_nop 1
	v_add_f32_dpp v68, v68, v68 row_half_mirror row_mask:0xf bank_mask:0xf bound_ctrl:1
	s_nop 1
	v_add_f32_dpp v68, v68, v68 row_mirror row_mask:0xf bank_mask:0xf bound_ctrl:1
	v_mov_b32_e32 v69, v68
	s_waitcnt lgkmcnt(0)
	s_nop 1
	v_permlane16_swap_b32_e32 v68, v69
	v_add_f32_e32 v68, v68, v69
	v_fmamk_f32 v68, v68, 0x3c000000, v234
	v_cmp_gt_f32_e32 vcc, s83, v68
	v_mul_f32_e32 v69, 0x4f800000, v68
	s_nop 0
	v_cndmask_b32_e32 v68, v68, v69, vcc
	v_sqrt_f32_e32 v69, v68
	s_nop 0
	v_add_u32_e32 v76, -1, v69
	v_fma_f32 v77, -v76, v69, v68
	v_cmp_ge_f32_e64 s[44:45], 0, v77
	v_add_u32_e32 v77, 1, v69
	s_nop 0
	v_cndmask_b32_e64 v76, v69, v76, s[44:45]
	v_fma_f32 v69, -v77, v69, v68
	v_cmp_lt_f32_e64 s[44:45], 0, v69
	s_nop 1
	v_cndmask_b32_e64 v69, v76, v77, s[44:45]
	v_mul_f32_e32 v76, 0x37800000, v69
	v_cndmask_b32_e32 v69, v69, v76, vcc
	v_cmp_class_f32_e32 vcc, v68, v235
	s_nop 1
	v_cndmask_b32_e32 v68, v69, v68, vcc
	v_div_scale_f32 v69, s[2:3], v68, v68, 1.0
	v_rcp_f32_e32 v76, v69
	s_nop 0
	v_fma_f32 v77, -v69, v76, 1.0
	v_fmac_f32_e32 v76, v77, v76
	v_div_scale_f32 v77, vcc, 1.0, v68, 1.0
	v_mul_f32_e32 v78, v77, v76
	v_fma_f32 v79, -v69, v78, v77
	v_fmac_f32_e32 v78, v79, v76
	v_fma_f32 v69, -v69, v78, v77
	v_div_fmas_f32 v69, v69, v76, v78
	v_div_fixup_f32 v76, v69, v68, 1.0
	v_pk_mul_f32 v[68:69], v[70:71], v[76:77] op_sel_hi:[1,0]
	v_pk_mul_f32 v[70:71], v[122:123], v[76:77] op_sel_hi:[1,0]
	v_pk_mul_f32 v[78:79], v[8:9], v[68:69]
	v_pk_mul_f32 v[76:77], v[10:11], v[70:71]
	v_pk_fma_f32 v[56:57], v[10:11], v[70:71], v[56:57]
	v_cvt_pk_f16_f32 v77, v76, v77
	v_cvt_pk_f16_f32 v76, v78, v79
	global_store_dwordx2 v[62:63], v[76:77], off offset:256
	v_pk_mul_f32 v[76:77], v[118:119], v[118:119]
	v_pk_mul_f32 v[78:79], v[120:121], v[120:121]
	v_add_f32_e32 v76, v76, v77
	v_add_f32_e32 v76, v78, v76
	v_add_f32_e32 v76, v79, v76
	v_pk_fma_f32 v[54:55], v[8:9], v[68:69], v[54:55]
	s_nop 0
	v_add_f32_dpp v76, v76, v76 quad_perm:[1,0,3,2] row_mask:0xf bank_mask:0xf bound_ctrl:1
	s_nop 1
	v_add_f32_dpp v76, v76, v76 quad_perm:[2,3,0,1] row_mask:0xf bank_mask:0xf bound_ctrl:1
	s_nop 1
	v_add_f32_dpp v76, v76, v76 row_half_mirror row_mask:0xf bank_mask:0xf bound_ctrl:1
	s_nop 1
	v_add_f32_dpp v76, v76, v76 row_mirror row_mask:0xf bank_mask:0xf bound_ctrl:1
	v_mov_b32_e32 v77, v76
	s_waitcnt lgkmcnt(0)
	s_nop 1
	v_permlane16_swap_b32_e32 v76, v77
	v_add_f32_e32 v76, v76, v77
	v_fmamk_f32 v76, v76, 0x3c000000, v234
	v_cmp_gt_f32_e32 vcc, s83, v76
	v_mul_f32_e32 v77, 0x4f800000, v76
	s_nop 0
	v_cndmask_b32_e32 v76, v76, v77, vcc
	v_sqrt_f32_e32 v77, v76
	s_nop 0
	v_add_u32_e32 v78, -1, v77
	v_fma_f32 v79, -v78, v77, v76
	v_cmp_ge_f32_e64 s[44:45], 0, v79
	v_add_u32_e32 v79, 1, v77
	s_nop 0
	v_cndmask_b32_e64 v78, v77, v78, s[44:45]
	v_fma_f32 v77, -v79, v77, v76
	v_cmp_lt_f32_e64 s[44:45], 0, v77
	s_nop 1
	v_cndmask_b32_e64 v77, v78, v79, s[44:45]
	v_mul_f32_e32 v78, 0x37800000, v77
	v_cndmask_b32_e32 v77, v77, v78, vcc
	v_cmp_class_f32_e32 vcc, v76, v235
	s_nop 1
	v_cndmask_b32_e32 v76, v77, v76, vcc
	v_div_scale_f32 v77, s[2:3], v76, v76, 1.0
	v_rcp_f32_e32 v78, v77
	s_nop 0
	v_fma_f32 v79, -v77, v78, 1.0
	v_fmac_f32_e32 v78, v79, v78
	v_div_scale_f32 v79, vcc, 1.0, v76, 1.0
	v_mul_f32_e32 v82, v79, v78
	v_fma_f32 v83, -v77, v82, v79
	v_fmac_f32_e32 v82, v83, v78
	v_fma_f32 v77, -v77, v82, v79
	v_div_fmas_f32 v77, v77, v78, v82
	v_div_fixup_f32 v78, v77, v76, 1.0
	v_pk_mul_f32 v[76:77], v[118:119], v[78:79] op_sel_hi:[1,0]
	v_pk_mul_f32 v[78:79], v[120:121], v[78:79] op_sel_hi:[1,0]
	v_pk_mul_f32 v[118:119], v[8:9], v[76:77]
	v_pk_mul_f32 v[82:83], v[10:11], v[78:79]
	v_pk_fma_f32 v[54:55], v[8:9], v[76:77], v[54:55]
	v_cvt_pk_f16_f32 v83, v82, v83
	v_cvt_pk_f16_f32 v82, v118, v119
	global_store_dwordx2 v[62:63], v[82:83], off offset:512
	v_pk_mul_f32 v[82:83], v[86:87], v[86:87]
	v_pk_mul_f32 v[118:119], v[116:117], v[116:117]
	v_add_f32_e32 v82, v82, v83
	v_add_f32_e32 v82, v118, v82
	v_add_f32_e32 v82, v119, v82
	v_pk_fma_f32 v[56:57], v[10:11], v[78:79], v[56:57]
	s_nop 0
	v_add_f32_dpp v82, v82, v82 quad_perm:[1,0,3,2] row_mask:0xf bank_mask:0xf bound_ctrl:1
	s_nop 1
	v_add_f32_dpp v82, v82, v82 quad_perm:[2,3,0,1] row_mask:0xf bank_mask:0xf bound_ctrl:1
	s_nop 1
	v_add_f32_dpp v82, v82, v82 row_half_mirror row_mask:0xf bank_mask:0xf bound_ctrl:1
	s_nop 1
	v_add_f32_dpp v82, v82, v82 row_mirror row_mask:0xf bank_mask:0xf bound_ctrl:1
	v_mov_b32_e32 v83, v82
	s_waitcnt lgkmcnt(0)
; __device__ __forceinline__ void phase_moba_prep(const Params& P, LAS unsigned char* lds, int l, int first, int stride) {
;     ...
;             for (int i = 0; i < 16; ++i) { const f16x4 t = raw[which][i]; v[i] = (f32x4){(float)t[0], (float)t[1], (float)t[2], (float)t[3]}; }
;             f32x4 cs = {0, 0, 0, 0};
; #pragma unroll
;             for (int i = 0; i < 16; ++i) {
;                 float ss = v[i][0] * v[i][0] + v[i][1] * v[i][1] + v[i][2] * v[i][2] + v[i][3] * v[i][3];
;                 ss = row_sum16(ss); ss += __shfl_xor(ss, 16);
;                 const float rstd = 1.0f / sqrtf(ss * (1.0f / HD) + EPS);
;                 f32x4 y = (v[i] * rstd) * gg;
;                 cs += y;
;                 if (which == 0) y = y * (0.08838834764831845f * 1.4426950408889634f);
;                 f16x4 o; o[0] = (f16)y[0]; o[1] = (f16)y[1]; o[2] = (f16)y[2]; o[3] = (f16)y[3];
;                 *(f16x4*)(dst + (size_t)i * HD) = o;
;             }
	s_nop 1
	v_permlane16_swap_b32_e32 v82, v83
	v_add_f32_e32 v82, v82, v83
	v_fmamk_f32 v82, v82, 0x3c000000, v234
	v_cmp_gt_f32_e32 vcc, s83, v82
	v_mul_f32_e32 v83, 0x4f800000, v82
	s_nop 0
	v_cndmask_b32_e32 v82, v82, v83, vcc
	v_sqrt_f32_e32 v83, v82
	s_nop 0
	v_add_u32_e32 v118, -1, v83
	v_fma_f32 v119, -v118, v83, v82
	v_cmp_ge_f32_e64 s[44:45], 0, v119
	v_add_u32_e32 v119, 1, v83
	s_nop 0
	v_cndmask_b32_e64 v118, v83, v118, s[44:45]
	v_fma_f32 v83, -v119, v83, v82
	v_cmp_lt_f32_e64 s[44:45], 0, v83
	s_nop 1
	v_cndmask_b32_e64 v83, v118, v119, s[44:45]
	v_mul_f32_e32 v118, 0x37800000, v83
	v_cndmask_b32_e32 v83, v83, v118, vcc
	v_cmp_class_f32_e32 vcc, v82, v235
	s_nop 1
	v_cndmask_b32_e32 v82, v83, v82, vcc
	v_div_scale_f32 v83, s[2:3], v82, v82, 1.0
	v_rcp_f32_e32 v118, v83
	s_nop 0
	v_fma_f32 v119, -v83, v118, 1.0
	v_fmac_f32_e32 v118, v119, v118
	v_div_scale_f32 v119, vcc, 1.0, v82, 1.0
	v_mul_f32_e32 v120, v119, v118
	v_fma_f32 v121, -v83, v120, v119
	v_fmac_f32_e32 v120, v121, v118
	v_fma_f32 v83, -v83, v120, v119
	v_div_fmas_f32 v83, v83, v118, v120
	v_div_fixup_f32 v118, v83, v82, 1.0
	v_pk_mul_f32 v[82:83], v[86:87], v[118:119] op_sel_hi:[1,0]
	v_pk_mul_f32 v[86:87], v[116:117], v[118:119] op_sel_hi:[1,0]
	v_pk_mul_f32 v[118:119], v[8:9], v[82:83]
	v_pk_mul_f32 v[116:117], v[10:11], v[86:87]
	v_pk_fma_f32 v[56:57], v[10:11], v[86:87], v[56:57]
	v_cvt_pk_f16_f32 v117, v116, v117
	v_cvt_pk_f16_f32 v116, v118, v119
	global_store_dwordx2 v[62:63], v[116:117], off offset:768
	v_pk_mul_f32 v[116:117], v[92:93], v[92:93]
	v_pk_mul_f32 v[118:119], v[94:95], v[94:95]
	v_add_f32_e32 v116, v116, v117
	v_add_f32_e32 v116, v118, v116
	v_add_f32_e32 v116, v119, v116
	v_pk_fma_f32 v[54:55], v[8:9], v[82:83], v[54:55]
	s_nop 0
	v_add_f32_dpp v116, v116, v116 quad_perm:[1,0,3,2] row_mask:0xf bank_mask:0xf bound_ctrl:1
	s_nop 1
	v_add_f32_dpp v116, v116, v116 quad_perm:[2,3,0,1] row_mask:0xf bank_mask:0xf bound_ctrl:1
	s_nop 1
	v_add_f32_dpp v116, v116, v116 row_half_mirror row_mask:0xf bank_mask:0xf bound_ctrl:1
	s_nop 1
	v_add_f32_dpp v116, v116, v116 row_mirror row_mask:0xf bank_mask:0xf bound_ctrl:1
	v_mov_b32_e32 v117, v116
	s_waitcnt lgkmcnt(0)
	s_nop 1
	v_permlane16_swap_b32_e32 v116, v117
	v_add_f32_e32 v116, v116, v117
	v_fmamk_f32 v116, v116, 0x3c000000, v234
	v_cmp_gt_f32_e32 vcc, s83, v116
	v_mul_f32_e32 v117, 0x4f800000, v116
	s_nop 0
	v_cndmask_b32_e32 v116, v116, v117, vcc
	v_sqrt_f32_e32 v117, v116
	s_nop 0
	v_add_u32_e32 v118, -1, v117
	v_fma_f32 v119, -v118, v117, v116
	v_cmp_ge_f32_e64 s[44:45], 0, v119
	v_add_u32_e32 v119, 1, v117
	s_nop 0
	v_cndmask_b32_e64 v118, v117, v118, s[44:45]
	v_fma_f32 v117, -v119, v117, v116
	v_cmp_lt_f32_e64 s[44:45], 0, v117
	s_nop 1
	v_cndmask_b32_e64 v117, v118, v119, s[44:45]
	v_mul_f32_e32 v118, 0x37800000, v117
	v_cndmask_b32_e32 v117, v117, v118, vcc
	v_cmp_class_f32_e32 vcc, v116, v235
	s_nop 1
	v_cndmask_b32_e32 v116, v117, v116, vcc
	v_div_scale_f32 v117, s[2:3], v116, v116, 1.0
	v_rcp_f32_e32 v118, v117
	s_nop 0
	v_fma_f32 v119, -v117, v118, 1.0
	v_fmac_f32_e32 v118, v119, v118
	v_div_scale_f32 v119, vcc, 1.0, v116, 1.0
	v_mul_f32_e32 v120, v119, v118
	v_fma_f32 v121, -v117, v120, v119
	v_fmac_f32_e32 v120, v121, v118
	v_fma_f32 v117, -v117, v120, v119
	v_div_fmas_f32 v117, v117, v118, v120
	v_div_fixup_f32 v116, v117, v116, 1.0
	v_pk_mul_f32 v[92:93], v[92:93], v[116:117] op_sel_hi:[1,0]
	v_pk_mul_f32 v[94:95], v[94:95], v[116:117] op_sel_hi:[1,0]
	v_pk_mul_f32 v[118:119], v[8:9], v[92:93]
	v_pk_mul_f32 v[116:117], v[10:11], v[94:95]
	v_pk_fma_f32 v[54:55], v[8:9], v[92:93], v[54:55]
	v_cvt_pk_f16_f32 v117, v116, v117
	v_cvt_pk_f16_f32 v116, v118, v119
	global_store_dwordx2 v[62:63], v[116:117], off offset:1024
	v_pk_mul_f32 v[116:117], v[100:101], v[100:101]
	v_pk_mul_f32 v[118:119], v[102:103], v[102:103]
	v_add_f32_e32 v116, v116, v117
	v_add_f32_e32 v116, v118, v116
	v_add_f32_e32 v116, v119, v116
	v_pk_fma_f32 v[56:57], v[10:11], v[94:95], v[56:57]
	s_nop 0
	v_add_f32_dpp v116, v116, v116 quad_perm:[1,0,3,2] row_mask:0xf bank_mask:0xf bound_ctrl:1
	s_nop 1
	v_add_f32_dpp v116, v116, v116 quad_perm:[2,3,0,1] row_mask:0xf bank_mask:0xf bound_ctrl:1
	s_nop 1
	v_add_f32_dpp v116, v116, v116 row_half_mirror row_mask:0xf bank_mask:0xf bound_ctrl:1
	s_nop 1
	v_add_f32_dpp v116, v116, v116 row_mirror row_mask:0xf bank_mask:0xf bound_ctrl:1
	v_mov_b32_e32 v117, v116
	s_waitcnt lgkmcnt(0)
	s_nop 1
	v_permlane16_swap_b32_e32 v116, v117
	v_add_f32_e32 v116, v116, v117
	v_fmamk_f32 v116, v116, 0x3c000000, v234
	v_cmp_gt_f32_e32 vcc, s83, v116
	v_mul_f32_e32 v117, 0x4f800000, v116
	s_nop 0
	v_cndmask_b32_e32 v116, v116, v117, vcc
	v_sqrt_f32_e32 v117, v116
	s_nop 0
	v_add_u32_e32 v118, -1, v117
	v_fma_f32 v119, -v118, v117, v116
	v_cmp_ge_f32_e64 s[44:45], 0, v119
	v_add_u32_e32 v119, 1, v117
	s_nop 0
	v_cndmask_b32_e64 v118, v117, v118, s[44:45]
	v_fma_f32 v117, -v119, v117, v116
	v_cmp_lt_f32_e64 s[44:45], 0, v117
	s_nop 1
	v_cndmask_b32_e64 v117, v118, v119, s[44:45]
	v_mul_f32_e32 v118, 0x37800000, v117
	v_cndmask_b32_e32 v117, v117, v118, vcc
	v_cmp_class_f32_e32 vcc, v116, v235
	s_nop 1
	v_cndmask_b32_e32 v116, v117, v116, vcc
	v_div_scale_f32 v117, s[2:3], v116, v116, 1.0
	v_rcp_f32_e32 v118, v117
	s_nop 0
	v_fma_f32 v119, -v117, v118, 1.0
	v_fmac_f32_e32 v118, v119, v118
	v_div_scale_f32 v119, vcc, 1.0, v116, 1.0
	v_mul_f32_e32 v120, v119, v118
	v_fma_f32 v121, -v117, v120, v119
	v_fmac_f32_e32 v120, v121, v118
	v_fma_f32 v117, -v117, v120, v119
	v_div_fmas_f32 v117, v117, v118, v120
	v_div_fixup_f32 v116, v117, v116, 1.0
	v_pk_mul_f32 v[100:101], v[100:101], v[116:117] op_sel_hi:[1,0]
	v_pk_mul_f32 v[102:103], v[102:103], v[116:117] op_sel_hi:[1,0]
	v_pk_mul_f32 v[118:119], v[8:9], v[100:101]
	v_pk_mul_f32 v[116:117], v[10:11], v[102:103]
	v_pk_fma_f32 v[56:57], v[10:11], v[102:103], v[56:57]
	v_cvt_pk_f16_f32 v117, v116, v117
	v_cvt_pk_f16_f32 v116, v118, v119
	global_store_dwordx2 v[62:63], v[116:117], off offset:1280
	v_pk_mul_f32 v[116:117], v[108:109], v[108:109]
	v_pk_mul_f32 v[118:119], v[110:111], v[110:111]
	v_add_f32_e32 v116, v116, v117
	v_add_f32_e32 v116, v118, v116
	v_add_f32_e32 v116, v119, v116
	v_pk_fma_f32 v[54:55], v[8:9], v[100:101], v[54:55]
	s_nop 0
	v_add_f32_dpp v116, v116, v116 quad_perm:[1,0,3,2] row_mask:0xf bank_mask:0xf bound_ctrl:1
	s_nop 1
	v_add_f32_dpp v116, v116, v116 quad_perm:[2,3,0,1] row_mask:0xf bank_mask:0xf bound_ctrl:1
	s_nop 1
	v_add_f32_dpp v116, v116, v116 row_half_mirror row_mask:0xf bank_mask:0xf bound_ctrl:1
	s_nop 1
	v_add_f32_dpp v116, v116, v116 row_mirror row_mask:0xf bank_mask:0xf bound_ctrl:1
	v_mov_b32_e32 v117, v116
	s_waitcnt lgkmcnt(0)
; __device__ __forceinline__ void phase_moba_prep(const Params& P, LAS unsigned char* lds, int l, int first, int stride) {
;     ...
;             for (int i = 0; i < 16; ++i) { const f16x4 t = raw[which][i]; v[i] = (f32x4){(float)t[0], (float)t[1], (float)t[2], (float)t[3]}; }
;             f32x4 cs = {0, 0, 0, 0};
; #pragma unroll
;             for (int i = 0; i < 16; ++i) {
;                 float ss = v[i][0] * v[i][0] + v[i][1] * v[i][1] + v[i][2] * v[i][2] + v[i][3] * v[i][3];
;                 ss = row_sum16(ss); ss += __shfl_xor(ss, 16);
;                 const float rstd = 1.0f / sqrtf(ss * (1.0f / HD) + EPS);
;                 f32x4 y = (v[i] * rstd) * gg;
;                 cs += y;
;                 if (which == 0) y = y * (0.08838834764831845f * 1.4426950408889634f);
;                 f16x4 o; o[0] = (f16)y[0]; o[1] = (f16)y[1]; o[2] = (f16)y[2]; o[3] = (f16)y[3];
;                 *(f16x4*)(dst + (size_t)i * HD) = o;
;             }
	s_nop 1
	v_permlane16_swap_b32_e32 v116, v117
	v_add_f32_e32 v116, v116, v117
	v_fmamk_f32 v116, v116, 0x3c000000, v234
	v_cmp_gt_f32_e32 vcc, s83, v116
	v_mul_f32_e32 v117, 0x4f800000, v116
	s_nop 0
	v_cndmask_b32_e32 v116, v116, v117, vcc
	v_sqrt_f32_e32 v117, v116
	s_nop 0
	v_add_u32_e32 v118, -1, v117
	v_fma_f32 v119, -v118, v117, v116
	v_cmp_ge_f32_e64 s[44:45], 0, v119
	v_add_u32_e32 v119, 1, v117
	s_nop 0
	v_cndmask_b32_e64 v118, v117, v118, s[44:45]
	v_fma_f32 v117, -v119, v117, v116
	v_cmp_lt_f32_e64 s[44:45], 0, v117
	s_nop 1
	v_cndmask_b32_e64 v117, v118, v119, s[44:45]
	v_mul_f32_e32 v118, 0x37800000, v117
	v_cndmask_b32_e32 v117, v117, v118, vcc
	v_cmp_class_f32_e32 vcc, v116, v235
	s_nop 1
	v_cndmask_b32_e32 v116, v117, v116, vcc
	v_div_scale_f32 v117, s[2:3], v116, v116, 1.0
	v_rcp_f32_e32 v118, v117
	s_nop 0
	v_fma_f32 v119, -v117, v118, 1.0
	v_fmac_f32_e32 v118, v119, v118
	v_div_scale_f32 v119, vcc, 1.0, v116, 1.0
	v_mul_f32_e32 v120, v119, v118
	v_fma_f32 v121, -v117, v120, v119
	v_fmac_f32_e32 v120, v121, v118
	v_fma_f32 v117, -v117, v120, v119
	v_div_fmas_f32 v117, v117, v118, v120
	v_div_fixup_f32 v116, v117, v116, 1.0
	v_pk_mul_f32 v[108:109], v[108:109], v[116:117] op_sel_hi:[1,0]
	v_pk_mul_f32 v[110:111], v[110:111], v[116:117] op_sel_hi:[1,0]
	v_pk_mul_f32 v[118:119], v[8:9], v[108:109]
	v_pk_mul_f32 v[116:117], v[10:11], v[110:111]
	v_pk_fma_f32 v[54:55], v[8:9], v[108:109], v[54:55]
	v_cvt_pk_f16_f32 v117, v116, v117
	v_cvt_pk_f16_f32 v116, v118, v119
	global_store_dwordx2 v[62:63], v[116:117], off offset:1536
	v_pk_mul_f32 v[116:117], v[112:113], v[112:113]
	v_pk_mul_f32 v[118:119], v[114:115], v[114:115]
	v_add_f32_e32 v116, v116, v117
	v_add_f32_e32 v116, v118, v116
	v_add_f32_e32 v116, v119, v116
	v_pk_fma_f32 v[56:57], v[10:11], v[110:111], v[56:57]
	s_nop 0
	v_add_f32_dpp v116, v116, v116 quad_perm:[1,0,3,2] row_mask:0xf bank_mask:0xf bound_ctrl:1
	s_nop 1
	v_add_f32_dpp v116, v116, v116 quad_perm:[2,3,0,1] row_mask:0xf bank_mask:0xf bound_ctrl:1
	s_nop 1
	v_add_f32_dpp v116, v116, v116 row_half_mirror row_mask:0xf bank_mask:0xf bound_ctrl:1
	s_nop 1
	v_add_f32_dpp v116, v116, v116 row_mirror row_mask:0xf bank_mask:0xf bound_ctrl:1
	v_mov_b32_e32 v117, v116
	s_waitcnt lgkmcnt(0)
	s_nop 1
	v_permlane16_swap_b32_e32 v116, v117
	v_add_f32_e32 v116, v116, v117
	v_fmamk_f32 v116, v116, 0x3c000000, v234
	v_cmp_gt_f32_e32 vcc, s83, v116
	v_mul_f32_e32 v117, 0x4f800000, v116
	s_nop 0
	v_cndmask_b32_e32 v116, v116, v117, vcc
	v_sqrt_f32_e32 v117, v116
	s_nop 0
	v_add_u32_e32 v118, -1, v117
	v_fma_f32 v119, -v118, v117, v116
	v_cmp_ge_f32_e64 s[44:45], 0, v119
	v_add_u32_e32 v119, 1, v117
	s_nop 0
	v_cndmask_b32_e64 v118, v117, v118, s[44:45]
	v_fma_f32 v117, -v119, v117, v116
	v_cmp_lt_f32_e64 s[44:45], 0, v117
	s_nop 1
	v_cndmask_b32_e64 v117, v118, v119, s[44:45]
	v_mul_f32_e32 v118, 0x37800000, v117
	v_cndmask_b32_e32 v117, v117, v118, vcc
	v_cmp_class_f32_e32 vcc, v116, v235
	s_nop 1
	v_cndmask_b32_e32 v116, v117, v116, vcc
	v_div_scale_f32 v117, s[2:3], v116, v116, 1.0
	v_rcp_f32_e32 v118, v117
	s_nop 0
	v_fma_f32 v119, -v117, v118, 1.0
	v_fmac_f32_e32 v118, v119, v118
	v_div_scale_f32 v119, vcc, 1.0, v116, 1.0
	v_mul_f32_e32 v120, v119, v118
	v_fma_f32 v121, -v117, v120, v119
	v_fmac_f32_e32 v120, v121, v118
	v_fma_f32 v117, -v117, v120, v119
	v_div_fmas_f32 v117, v117, v118, v120
	v_div_fixup_f32 v116, v117, v116, 1.0
	v_pk_mul_f32 v[112:113], v[112:113], v[116:117] op_sel_hi:[1,0]
	v_pk_mul_f32 v[114:115], v[114:115], v[116:117] op_sel_hi:[1,0]
	v_pk_mul_f32 v[118:119], v[8:9], v[112:113]
	v_pk_mul_f32 v[116:117], v[10:11], v[114:115]
	v_pk_fma_f32 v[56:57], v[10:11], v[114:115], v[56:57]
	v_cvt_pk_f16_f32 v117, v116, v117
	v_cvt_pk_f16_f32 v116, v118, v119
	global_store_dwordx2 v[62:63], v[116:117], off offset:1792
	v_pk_mul_f32 v[116:117], v[104:105], v[104:105]
	v_pk_mul_f32 v[118:119], v[106:107], v[106:107]
	v_add_f32_e32 v116, v116, v117
	v_add_f32_e32 v116, v118, v116
	v_add_f32_e32 v116, v119, v116
	v_pk_fma_f32 v[54:55], v[8:9], v[112:113], v[54:55]
	s_nop 0
	v_add_f32_dpp v116, v116, v116 quad_perm:[1,0,3,2] row_mask:0xf bank_mask:0xf bound_ctrl:1
	s_nop 1
	v_add_f32_dpp v116, v116, v116 quad_perm:[2,3,0,1] row_mask:0xf bank_mask:0xf bound_ctrl:1
	s_nop 1
	v_add_f32_dpp v116, v116, v116 row_half_mirror row_mask:0xf bank_mask:0xf bound_ctrl:1
	s_nop 1
	v_add_f32_dpp v116, v116, v116 row_mirror row_mask:0xf bank_mask:0xf bound_ctrl:1
	v_mov_b32_e32 v117, v116
	s_waitcnt lgkmcnt(0)
	s_nop 1
	v_permlane16_swap_b32_e32 v116, v117
	v_add_f32_e32 v116, v116, v117
	v_fmamk_f32 v116, v116, 0x3c000000, v234
	v_cmp_gt_f32_e32 vcc, s83, v116
	v_mul_f32_e32 v117, 0x4f800000, v116
	s_nop 0
	v_cndmask_b32_e32 v116, v116, v117, vcc
	v_sqrt_f32_e32 v117, v116
	s_nop 0
	v_add_u32_e32 v118, -1, v117
	v_fma_f32 v119, -v118, v117, v116
	v_cmp_ge_f32_e64 s[44:45], 0, v119
	v_add_u32_e32 v119, 1, v117
	s_nop 0
	v_cndmask_b32_e64 v118, v117, v118, s[44:45]
	v_fma_f32 v117, -v119, v117, v116
	v_cmp_lt_f32_e64 s[44:45], 0, v117
	s_nop 1
	v_cndmask_b32_e64 v117, v118, v119, s[44:45]
	v_mul_f32_e32 v118, 0x37800000, v117
	v_cndmask_b32_e32 v117, v117, v118, vcc
	v_cmp_class_f32_e32 vcc, v116, v235
	s_nop 1
	v_cndmask_b32_e32 v116, v117, v116, vcc
	v_div_scale_f32 v117, s[2:3], v116, v116, 1.0
	v_rcp_f32_e32 v118, v117
	s_nop 0
	v_fma_f32 v119, -v117, v118, 1.0
	v_fmac_f32_e32 v118, v119, v118
	v_div_scale_f32 v119, vcc, 1.0, v116, 1.0
	v_mul_f32_e32 v120, v119, v118
	v_fma_f32 v121, -v117, v120, v119
	v_fmac_f32_e32 v120, v121, v118
	v_fma_f32 v117, -v117, v120, v119
	v_div_fmas_f32 v117, v117, v118, v120
	v_div_fixup_f32 v116, v117, v116, 1.0
	v_pk_mul_f32 v[104:105], v[104:105], v[116:117] op_sel_hi:[1,0]
	v_pk_mul_f32 v[106:107], v[106:107], v[116:117] op_sel_hi:[1,0]
	v_pk_mul_f32 v[118:119], v[8:9], v[104:105]
	v_pk_mul_f32 v[116:117], v[10:11], v[106:107]
	v_pk_fma_f32 v[54:55], v[8:9], v[104:105], v[54:55]
	v_cvt_pk_f16_f32 v117, v116, v117
	v_cvt_pk_f16_f32 v116, v118, v119
	global_store_dwordx2 v[62:63], v[116:117], off offset:2048
	v_pk_mul_f32 v[116:117], v[96:97], v[96:97]
	v_pk_mul_f32 v[118:119], v[98:99], v[98:99]
	v_add_f32_e32 v116, v116, v117
	v_add_f32_e32 v116, v118, v116
	v_add_f32_e32 v116, v119, v116
	v_pk_fma_f32 v[56:57], v[10:11], v[106:107], v[56:57]
	s_nop 0
	v_add_f32_dpp v116, v116, v116 quad_perm:[1,0,3,2] row_mask:0xf bank_mask:0xf bound_ctrl:1
	s_nop 1
	v_add_f32_dpp v116, v116, v116 quad_perm:[2,3,0,1] row_mask:0xf bank_mask:0xf bound_ctrl:1
	s_nop 1
	v_add_f32_dpp v116, v116, v116 row_half_mirror row_mask:0xf bank_mask:0xf bound_ctrl:1
	s_nop 1
	v_add_f32_dpp v116, v116, v116 row_mirror row_mask:0xf bank_mask:0xf bound_ctrl:1
	v_mov_b32_e32 v117, v116
	s_waitcnt lgkmcnt(0)
; __device__ __forceinline__ void phase_moba_prep(const Params& P, LAS unsigned char* lds, int l, int first, int stride) {
;     ...
;             for (int i = 0; i < 16; ++i) { const f16x4 t = raw[which][i]; v[i] = (f32x4){(float)t[0], (float)t[1], (float)t[2], (float)t[3]}; }
;             f32x4 cs = {0, 0, 0, 0};
; #pragma unroll
;             for (int i = 0; i < 16; ++i) {
;                 float ss = v[i][0] * v[i][0] + v[i][1] * v[i][1] + v[i][2] * v[i][2] + v[i][3] * v[i][3];
;                 ss = row_sum16(ss); ss += __shfl_xor(ss, 16);
;                 const float rstd = 1.0f / sqrtf(ss * (1.0f / HD) + EPS);
;                 f32x4 y = (v[i] * rstd) * gg;
;                 cs += y;
;                 if (which == 0) y = y * (0.08838834764831845f * 1.4426950408889634f);
;                 f16x4 o; o[0] = (f16)y[0]; o[1] = (f16)y[1]; o[2] = (f16)y[2]; o[3] = (f16)y[3];
;                 *(f16x4*)(dst + (size_t)i * HD) = o;
;             }
	s_nop 1
	v_permlane16_swap_b32_e32 v116, v117
	v_add_f32_e32 v116, v116, v117
	v_fmamk_f32 v116, v116, 0x3c000000, v234
	v_cmp_gt_f32_e32 vcc, s83, v116
	v_mul_f32_e32 v117, 0x4f800000, v116
	s_nop 0
	v_cndmask_b32_e32 v116, v116, v117, vcc
	v_sqrt_f32_e32 v117, v116
	s_nop 0
	v_add_u32_e32 v118, -1, v117
	v_fma_f32 v119, -v118, v117, v116
	v_cmp_ge_f32_e64 s[44:45], 0, v119
	v_add_u32_e32 v119, 1, v117
	s_nop 0
	v_cndmask_b32_e64 v118, v117, v118, s[44:45]
	v_fma_f32 v117, -v119, v117, v116
	v_cmp_lt_f32_e64 s[44:45], 0, v117
	s_nop 1
	v_cndmask_b32_e64 v117, v118, v119, s[44:45]
	v_mul_f32_e32 v118, 0x37800000, v117
	v_cndmask_b32_e32 v117, v117, v118, vcc
	v_cmp_class_f32_e32 vcc, v116, v235
	s_nop 1
	v_cndmask_b32_e32 v116, v117, v116, vcc
	v_div_scale_f32 v117, s[2:3], v116, v116, 1.0
	v_rcp_f32_e32 v118, v117
	s_nop 0
	v_fma_f32 v119, -v117, v118, 1.0
	v_fmac_f32_e32 v118, v119, v118
	v_div_scale_f32 v119, vcc, 1.0, v116, 1.0
	v_mul_f32_e32 v120, v119, v118
	v_fma_f32 v121, -v117, v120, v119
	v_fmac_f32_e32 v120, v121, v118
	v_fma_f32 v117, -v117, v120, v119
	v_div_fmas_f32 v117, v117, v118, v120
	v_div_fixup_f32 v116, v117, v116, 1.0
	v_pk_mul_f32 v[96:97], v[96:97], v[116:117] op_sel_hi:[1,0]
	v_pk_mul_f32 v[98:99], v[98:99], v[116:117] op_sel_hi:[1,0]
	v_pk_mul_f32 v[118:119], v[8:9], v[96:97]
	v_pk_mul_f32 v[116:117], v[10:11], v[98:99]
	v_pk_fma_f32 v[56:57], v[10:11], v[98:99], v[56:57]
	v_cvt_pk_f16_f32 v117, v116, v117
	v_cvt_pk_f16_f32 v116, v118, v119
	global_store_dwordx2 v[62:63], v[116:117], off offset:2304
	v_pk_mul_f32 v[116:117], v[88:89], v[88:89]
	v_pk_mul_f32 v[118:119], v[90:91], v[90:91]
	v_add_f32_e32 v116, v116, v117
	v_add_f32_e32 v116, v118, v116
	v_add_f32_e32 v116, v119, v116
	v_pk_fma_f32 v[54:55], v[8:9], v[96:97], v[54:55]
	s_nop 0
	v_add_f32_dpp v116, v116, v116 quad_perm:[1,0,3,2] row_mask:0xf bank_mask:0xf bound_ctrl:1
	s_nop 1
	v_add_f32_dpp v116, v116, v116 quad_perm:[2,3,0,1] row_mask:0xf bank_mask:0xf bound_ctrl:1
	s_nop 1
	v_add_f32_dpp v116, v116, v116 row_half_mirror row_mask:0xf bank_mask:0xf bound_ctrl:1
	s_nop 1
	v_add_f32_dpp v116, v116, v116 row_mirror row_mask:0xf bank_mask:0xf bound_ctrl:1
	v_mov_b32_e32 v117, v116
	s_waitcnt lgkmcnt(0)
	s_nop 1
	v_permlane16_swap_b32_e32 v116, v117
	v_add_f32_e32 v116, v116, v117
	v_fmamk_f32 v116, v116, 0x3c000000, v234
	v_cmp_gt_f32_e32 vcc, s83, v116
	v_mul_f32_e32 v117, 0x4f800000, v116
	s_nop 0
	v_cndmask_b32_e32 v116, v116, v117, vcc
	v_sqrt_f32_e32 v117, v116
	s_nop 0
	v_add_u32_e32 v118, -1, v117
	v_fma_f32 v119, -v118, v117, v116
	v_cmp_ge_f32_e64 s[44:45], 0, v119
	v_add_u32_e32 v119, 1, v117
	s_nop 0
	v_cndmask_b32_e64 v118, v117, v118, s[44:45]
	v_fma_f32 v117, -v119, v117, v116
	v_cmp_lt_f32_e64 s[44:45], 0, v117
	s_nop 1
	v_cndmask_b32_e64 v117, v118, v119, s[44:45]
	v_mul_f32_e32 v118, 0x37800000, v117
	v_cndmask_b32_e32 v117, v117, v118, vcc
	v_cmp_class_f32_e32 vcc, v116, v235
	s_nop 1
	v_cndmask_b32_e32 v116, v117, v116, vcc
	v_div_scale_f32 v117, s[2:3], v116, v116, 1.0
	v_rcp_f32_e32 v118, v117
	s_nop 0
	v_fma_f32 v119, -v117, v118, 1.0
	v_fmac_f32_e32 v118, v119, v118
	v_div_scale_f32 v119, vcc, 1.0, v116, 1.0
	v_mul_f32_e32 v120, v119, v118
	v_fma_f32 v121, -v117, v120, v119
	v_fmac_f32_e32 v120, v121, v118
	v_fma_f32 v117, -v117, v120, v119
	v_div_fmas_f32 v117, v117, v118, v120
	v_div_fixup_f32 v116, v117, v116, 1.0
	v_pk_mul_f32 v[88:89], v[88:89], v[116:117] op_sel_hi:[1,0]
	v_pk_mul_f32 v[90:91], v[90:91], v[116:117] op_sel_hi:[1,0]
	v_pk_mul_f32 v[118:119], v[8:9], v[88:89]
	v_pk_mul_f32 v[116:117], v[10:11], v[90:91]
	v_pk_fma_f32 v[54:55], v[8:9], v[88:89], v[54:55]
	v_cvt_pk_f16_f32 v117, v116, v117
	v_cvt_pk_f16_f32 v116, v118, v119
	global_store_dwordx2 v[62:63], v[116:117], off offset:2560
	v_pk_mul_f32 v[116:117], v[80:81], v[80:81]
	v_pk_mul_f32 v[118:119], v[84:85], v[84:85]
	v_add_f32_e32 v116, v116, v117
	v_add_f32_e32 v116, v118, v116
	v_add_f32_e32 v116, v119, v116
	v_pk_fma_f32 v[56:57], v[10:11], v[90:91], v[56:57]
	s_nop 0
	v_add_f32_dpp v116, v116, v116 quad_perm:[1,0,3,2] row_mask:0xf bank_mask:0xf bound_ctrl:1
	s_nop 1
	v_add_f32_dpp v116, v116, v116 quad_perm:[2,3,0,1] row_mask:0xf bank_mask:0xf bound_ctrl:1
	s_nop 1
	v_add_f32_dpp v116, v116, v116 row_half_mirror row_mask:0xf bank_mask:0xf bound_ctrl:1
	s_nop 1
	v_add_f32_dpp v116, v116, v116 row_mirror row_mask:0xf bank_mask:0xf bound_ctrl:1
	v_mov_b32_e32 v117, v116
	s_waitcnt lgkmcnt(0)
	s_nop 1
	v_permlane16_swap_b32_e32 v116, v117
	v_add_f32_e32 v116, v116, v117
	v_fmamk_f32 v116, v116, 0x3c000000, v234
	v_cmp_gt_f32_e32 vcc, s83, v116
	v_mul_f32_e32 v117, 0x4f800000, v116
	s_nop 0
	v_cndmask_b32_e32 v116, v116, v117, vcc
	v_sqrt_f32_e32 v117, v116
	s_nop 0
	v_add_u32_e32 v118, -1, v117
	v_fma_f32 v119, -v118, v117, v116
	v_cmp_ge_f32_e64 s[44:45], 0, v119
	v_add_u32_e32 v119, 1, v117
	s_nop 0
	v_cndmask_b32_e64 v118, v117, v118, s[44:45]
	v_fma_f32 v117, -v119, v117, v116
	v_cmp_lt_f32_e64 s[44:45], 0, v117
	s_nop 1
	v_cndmask_b32_e64 v117, v118, v119, s[44:45]
	v_mul_f32_e32 v118, 0x37800000, v117
	v_cndmask_b32_e32 v117, v117, v118, vcc
	v_cmp_class_f32_e32 vcc, v116, v235
	s_nop 1
	v_cndmask_b32_e32 v116, v117, v116, vcc
	v_div_scale_f32 v117, s[2:3], v116, v116, 1.0
	v_rcp_f32_e32 v118, v117
	s_nop 0
	v_fma_f32 v119, -v117, v118, 1.0
	v_fmac_f32_e32 v118, v119, v118
	v_div_scale_f32 v119, vcc, 1.0, v116, 1.0
	v_mul_f32_e32 v120, v119, v118
	v_fma_f32 v121, -v117, v120, v119
	v_fmac_f32_e32 v120, v121, v118
	v_fma_f32 v117, -v117, v120, v119
	v_div_fmas_f32 v117, v117, v118, v120
	v_div_fixup_f32 v116, v117, v116, 1.0
	v_pk_mul_f32 v[80:81], v[80:81], v[116:117] op_sel_hi:[1,0]
	v_pk_mul_f32 v[84:85], v[84:85], v[116:117] op_sel_hi:[1,0]
	v_pk_mul_f32 v[118:119], v[8:9], v[80:81]
	v_pk_mul_f32 v[116:117], v[10:11], v[84:85]
	v_pk_fma_f32 v[56:57], v[10:11], v[84:85], v[56:57]
	v_cvt_pk_f16_f32 v117, v116, v117
	v_cvt_pk_f16_f32 v116, v118, v119
	global_store_dwordx2 v[62:63], v[116:117], off offset:2816
	v_pk_mul_f32 v[116:117], v[74:75], v[74:75]
	v_pk_mul_f32 v[118:119], v[72:73], v[72:73]
	v_add_f32_e32 v116, v116, v117
	v_add_f32_e32 v116, v118, v116
	v_add_f32_e32 v116, v119, v116
	v_pk_fma_f32 v[54:55], v[8:9], v[80:81], v[54:55]
	s_nop 0
	v_add_f32_dpp v116, v116, v116 quad_perm:[1,0,3,2] row_mask:0xf bank_mask:0xf bound_ctrl:1
	s_nop 1
	v_add_f32_dpp v116, v116, v116 quad_perm:[2,3,0,1] row_mask:0xf bank_mask:0xf bound_ctrl:1
	s_nop 1
	v_add_f32_dpp v116, v116, v116 row_half_mirror row_mask:0xf bank_mask:0xf bound_ctrl:1
	s_nop 1
	v_add_f32_dpp v116, v116, v116 row_mirror row_mask:0xf bank_mask:0xf bound_ctrl:1
	v_mov_b32_e32 v117, v116
	s_waitcnt lgkmcnt(0)
; __device__ __forceinline__ void phase_moba_prep(const Params& P, LAS unsigned char* lds, int l, int first, int stride) {
;     ...
;             for (int i = 0; i < 16; ++i) { const f16x4 t = raw[which][i]; v[i] = (f32x4){(float)t[0], (float)t[1], (float)t[2], (float)t[3]}; }
;             f32x4 cs = {0, 0, 0, 0};
; #pragma unroll
;             for (int i = 0; i < 16; ++i) {
;                 float ss = v[i][0] * v[i][0] + v[i][1] * v[i][1] + v[i][2] * v[i][2] + v[i][3] * v[i][3];
;                 ss = row_sum16(ss); ss += __shfl_xor(ss, 16);
;                 const float rstd = 1.0f / sqrtf(ss * (1.0f / HD) + EPS);
;                 f32x4 y = (v[i] * rstd) * gg;
;                 cs += y;
;                 if (which == 0) y = y * (0.08838834764831845f * 1.4426950408889634f);
;                 f16x4 o; o[0] = (f16)y[0]; o[1] = (f16)y[1]; o[2] = (f16)y[2]; o[3] = (f16)y[3];
;                 *(f16x4*)(dst + (size_t)i * HD) = o;
;             }
	s_nop 1
	v_permlane16_swap_b32_e32 v116, v117
	v_add_f32_e32 v116, v116, v117
	v_fmamk_f32 v116, v116, 0x3c000000, v234
	v_cmp_gt_f32_e32 vcc, s83, v116
	v_mul_f32_e32 v117, 0x4f800000, v116
	s_nop 0
	v_cndmask_b32_e32 v116, v116, v117, vcc
	v_sqrt_f32_e32 v117, v116
	s_nop 0
	v_add_u32_e32 v118, -1, v117
	v_fma_f32 v119, -v118, v117, v116
	v_cmp_ge_f32_e64 s[44:45], 0, v119
	v_add_u32_e32 v119, 1, v117
	s_nop 0
	v_cndmask_b32_e64 v118, v117, v118, s[44:45]
	v_fma_f32 v117, -v119, v117, v116
	v_cmp_lt_f32_e64 s[44:45], 0, v117
	s_nop 1
	v_cndmask_b32_e64 v117, v118, v119, s[44:45]
	v_mul_f32_e32 v118, 0x37800000, v117
	v_cndmask_b32_e32 v117, v117, v118, vcc
	v_cmp_class_f32_e32 vcc, v116, v235
	s_nop 1
	v_cndmask_b32_e32 v116, v117, v116, vcc
	v_div_scale_f32 v117, s[2:3], v116, v116, 1.0
	v_rcp_f32_e32 v118, v117
	s_nop 0
	v_fma_f32 v119, -v117, v118, 1.0
	v_fmac_f32_e32 v118, v119, v118
	v_div_scale_f32 v119, vcc, 1.0, v116, 1.0
	v_mul_f32_e32 v120, v119, v118
	v_fma_f32 v121, -v117, v120, v119
	v_fmac_f32_e32 v120, v121, v118
	v_fma_f32 v117, -v117, v120, v119
	v_div_fmas_f32 v117, v117, v118, v120
	v_div_fixup_f32 v116, v117, v116, 1.0
	v_pk_mul_f32 v[74:75], v[74:75], v[116:117] op_sel_hi:[1,0]
	v_pk_mul_f32 v[72:73], v[72:73], v[116:117] op_sel_hi:[1,0]
	v_pk_mul_f32 v[118:119], v[8:9], v[74:75]
	v_pk_mul_f32 v[116:117], v[10:11], v[72:73]
	v_pk_fma_f32 v[54:55], v[8:9], v[74:75], v[54:55]
	v_cvt_pk_f16_f32 v117, v116, v117
	v_cvt_pk_f16_f32 v116, v118, v119
	global_store_dwordx2 v[62:63], v[116:117], off offset:3072
	v_pk_mul_f32 v[116:117], v[66:67], v[66:67]
	v_pk_mul_f32 v[118:119], v[64:65], v[64:65]
	v_add_f32_e32 v116, v116, v117
	v_add_f32_e32 v116, v118, v116
	v_add_f32_e32 v116, v119, v116
	v_pk_fma_f32 v[56:57], v[10:11], v[72:73], v[56:57]
	s_nop 0
	v_add_f32_dpp v116, v116, v116 quad_perm:[1,0,3,2] row_mask:0xf bank_mask:0xf bound_ctrl:1
	s_nop 1
	v_add_f32_dpp v116, v116, v116 quad_perm:[2,3,0,1] row_mask:0xf bank_mask:0xf bound_ctrl:1
	s_nop 1
	v_add_f32_dpp v116, v116, v116 row_half_mirror row_mask:0xf bank_mask:0xf bound_ctrl:1
	s_nop 1
	v_add_f32_dpp v116, v116, v116 row_mirror row_mask:0xf bank_mask:0xf bound_ctrl:1
	v_mov_b32_e32 v117, v116
	s_waitcnt lgkmcnt(0)
	s_nop 1
	v_permlane16_swap_b32_e32 v116, v117
	v_add_f32_e32 v116, v116, v117
	v_fmamk_f32 v116, v116, 0x3c000000, v234
	v_cmp_gt_f32_e32 vcc, s83, v116
	v_mul_f32_e32 v117, 0x4f800000, v116
	s_nop 0
	v_cndmask_b32_e32 v116, v116, v117, vcc
	v_sqrt_f32_e32 v117, v116
	s_nop 0
	v_add_u32_e32 v118, -1, v117
	v_fma_f32 v119, -v118, v117, v116
	v_cmp_ge_f32_e64 s[44:45], 0, v119
	v_add_u32_e32 v119, 1, v117
	s_nop 0
	v_cndmask_b32_e64 v118, v117, v118, s[44:45]
	v_fma_f32 v117, -v119, v117, v116
	v_cmp_lt_f32_e64 s[44:45], 0, v117
	s_nop 1
	v_cndmask_b32_e64 v117, v118, v119, s[44:45]
	v_mul_f32_e32 v118, 0x37800000, v117
	v_cndmask_b32_e32 v117, v117, v118, vcc
	v_cmp_class_f32_e32 vcc, v116, v235
	s_nop 1
	v_cndmask_b32_e32 v116, v117, v116, vcc
	v_div_scale_f32 v117, s[2:3], v116, v116, 1.0
	v_rcp_f32_e32 v118, v117
	s_nop 0
	v_fma_f32 v119, -v117, v118, 1.0
	v_fmac_f32_e32 v118, v119, v118
	v_div_scale_f32 v119, vcc, 1.0, v116, 1.0
	v_mul_f32_e32 v120, v119, v118
	v_fma_f32 v121, -v117, v120, v119
	v_fmac_f32_e32 v120, v121, v118
	v_fma_f32 v117, -v117, v120, v119
	v_div_fmas_f32 v117, v117, v118, v120
	v_div_fixup_f32 v116, v117, v116, 1.0
	v_pk_mul_f32 v[66:67], v[66:67], v[116:117] op_sel_hi:[1,0]
	v_pk_mul_f32 v[64:65], v[64:65], v[116:117] op_sel_hi:[1,0]
	v_pk_mul_f32 v[118:119], v[8:9], v[66:67]
	v_pk_mul_f32 v[116:117], v[10:11], v[64:65]
	v_pk_fma_f32 v[56:57], v[10:11], v[64:65], v[56:57]
	v_cvt_pk_f16_f32 v117, v116, v117
	v_cvt_pk_f16_f32 v116, v118, v119
	global_store_dwordx2 v[62:63], v[116:117], off offset:3328
	v_pk_mul_f32 v[116:117], v[58:59], v[58:59]
	v_pk_mul_f32 v[118:119], v[60:61], v[60:61]
	v_add_f32_e32 v116, v116, v117
	v_add_f32_e32 v116, v118, v116
	v_add_f32_e32 v116, v119, v116
	v_pk_fma_f32 v[54:55], v[8:9], v[66:67], v[54:55]
	s_nop 0
	v_add_f32_dpp v116, v116, v116 quad_perm:[1,0,3,2] row_mask:0xf bank_mask:0xf bound_ctrl:1
	s_nop 1
	v_add_f32_dpp v116, v116, v116 quad_perm:[2,3,0,1] row_mask:0xf bank_mask:0xf bound_ctrl:1
	s_nop 1
	v_add_f32_dpp v116, v116, v116 row_half_mirror row_mask:0xf bank_mask:0xf bound_ctrl:1
	s_nop 1
	v_add_f32_dpp v116, v116, v116 row_mirror row_mask:0xf bank_mask:0xf bound_ctrl:1
	v_mov_b32_e32 v117, v116
	s_waitcnt lgkmcnt(0)
; __device__ __forceinline__ void phase_moba_prep(const Params& P, LAS unsigned char* lds, int l, int first, int stride) {
;     ...
;             for (int i = 0; i < 16; ++i) {
;                 float ss = v[i][0] * v[i][0] + v[i][1] * v[i][1] + v[i][2] * v[i][2] + v[i][3] * v[i][3];
;                 ss = row_sum16(ss); ss += __shfl_xor(ss, 16);
;                 const float rstd = 1.0f / sqrtf(ss * (1.0f / HD) + EPS);
;                 f32x4 y = (v[i] * rstd) * gg;
;                 cs += y;
;                 if (which == 0) y = y * (0.08838834764831845f * 1.4426950408889634f);
;                 f16x4 o; o[0] = (f16)y[0]; o[1] = (f16)y[1]; o[2] = (f16)y[2]; o[3] = (f16)y[3];
;                 *(f16x4*)(dst + (size_t)i * HD) = o;
;             }
;             if (which == 1) {
; #pragma unroll
;                 for (int e = 0; e < 4; ++e) red[tg * 128 + 4 * d4 + e] = cs[e];
;                 __syncthreads();
;                 if (tid < 128) { float s = 0.f;
; #pragma unroll
;                     for (int q = 0; q < 16; ++q) s += red[q * 128 + tid];
;                     kmean[((size_t)(bh * NBLK + j)) * HD + tid] = s * (1.0f / 256.0f); }
;                 __syncthreads();
	s_nop 1
	v_permlane16_swap_b32_e32 v116, v117
	v_add_f32_e32 v116, v116, v117
	v_fmamk_f32 v116, v116, 0x3c000000, v234
	v_cmp_gt_f32_e32 vcc, s83, v116
	v_mul_f32_e32 v117, 0x4f800000, v116
	s_nop 0
	v_cndmask_b32_e32 v116, v116, v117, vcc
	v_sqrt_f32_e32 v117, v116
	s_nop 0
	v_add_u32_e32 v118, -1, v117
	v_fma_f32 v119, -v118, v117, v116
	v_cmp_ge_f32_e64 s[44:45], 0, v119
	v_add_u32_e32 v119, 1, v117
	s_nop 0
	v_cndmask_b32_e64 v118, v117, v118, s[44:45]
	v_fma_f32 v117, -v119, v117, v116
	v_cmp_lt_f32_e64 s[44:45], 0, v117
	s_nop 1
	v_cndmask_b32_e64 v117, v118, v119, s[44:45]
	v_mul_f32_e32 v118, 0x37800000, v117
	v_cndmask_b32_e32 v117, v117, v118, vcc
	v_cmp_class_f32_e32 vcc, v116, v235
	s_nop 1
	v_cndmask_b32_e32 v116, v117, v116, vcc
	v_div_scale_f32 v117, s[2:3], v116, v116, 1.0
	v_rcp_f32_e32 v118, v117
	s_nop 0
	v_fma_f32 v119, -v117, v118, 1.0
	v_fmac_f32_e32 v118, v119, v118
	v_div_scale_f32 v119, vcc, 1.0, v116, 1.0
	v_mul_f32_e32 v120, v119, v118
	v_fma_f32 v121, -v117, v120, v119
	v_fmac_f32_e32 v120, v121, v118
	v_fma_f32 v117, -v117, v120, v119
	v_div_fmas_f32 v117, v117, v118, v120
	v_div_fixup_f32 v116, v117, v116, 1.0
	v_pk_mul_f32 v[58:59], v[58:59], v[116:117] op_sel_hi:[1,0]
	v_pk_mul_f32 v[60:61], v[60:61], v[116:117] op_sel_hi:[1,0]
	v_pk_mul_f32 v[118:119], v[8:9], v[58:59]
	v_pk_mul_f32 v[116:117], v[10:11], v[60:61]
	v_pk_fma_f32 v[54:55], v[8:9], v[58:59], v[54:55]
	v_cvt_pk_f16_f32 v117, v116, v117
	v_cvt_pk_f16_f32 v116, v118, v119
	global_store_dwordx2 v[62:63], v[116:117], off offset:3584
	v_pk_mul_f32 v[116:117], v[50:51], v[50:51]
	v_pk_mul_f32 v[118:119], v[52:53], v[52:53]
	v_add_f32_e32 v116, v116, v117
	v_add_f32_e32 v116, v118, v116
	v_add_f32_e32 v116, v119, v116
	v_pk_fma_f32 v[56:57], v[10:11], v[60:61], v[56:57]
	s_nop 0
	v_add_f32_dpp v116, v116, v116 quad_perm:[1,0,3,2] row_mask:0xf bank_mask:0xf bound_ctrl:1
	s_nop 1
	v_add_f32_dpp v116, v116, v116 quad_perm:[2,3,0,1] row_mask:0xf bank_mask:0xf bound_ctrl:1
	s_nop 1
	v_add_f32_dpp v116, v116, v116 row_half_mirror row_mask:0xf bank_mask:0xf bound_ctrl:1
	s_nop 1
	v_add_f32_dpp v116, v116, v116 row_mirror row_mask:0xf bank_mask:0xf bound_ctrl:1
	v_mov_b32_e32 v117, v116
	s_waitcnt lgkmcnt(0)
	s_nop 1
	v_permlane16_swap_b32_e32 v116, v117
	v_add_f32_e32 v116, v116, v117
	v_fmamk_f32 v116, v116, 0x3c000000, v234
	v_cmp_gt_f32_e32 vcc, s83, v116
	v_mul_f32_e32 v117, 0x4f800000, v116
	s_nop 0
	v_cndmask_b32_e32 v116, v116, v117, vcc
	v_sqrt_f32_e32 v117, v116
	s_nop 0
	v_add_u32_e32 v118, -1, v117
	v_fma_f32 v119, -v118, v117, v116
	v_cmp_ge_f32_e64 s[44:45], 0, v119
	v_add_u32_e32 v119, 1, v117
	s_nop 0
	v_cndmask_b32_e64 v118, v117, v118, s[44:45]
	v_fma_f32 v117, -v119, v117, v116
	v_cmp_lt_f32_e64 s[44:45], 0, v117
	s_nop 1
	v_cndmask_b32_e64 v117, v118, v119, s[44:45]
	v_mul_f32_e32 v118, 0x37800000, v117
	v_cndmask_b32_e32 v117, v117, v118, vcc
	v_cmp_class_f32_e32 vcc, v116, v235
	s_nop 1
	v_cndmask_b32_e32 v116, v117, v116, vcc
	v_div_scale_f32 v117, s[2:3], v116, v116, 1.0
	v_rcp_f32_e32 v118, v117
	s_nop 0
	v_fma_f32 v119, -v117, v118, 1.0
	v_fmac_f32_e32 v118, v119, v118
	v_div_scale_f32 v119, vcc, 1.0, v116, 1.0
	v_mul_f32_e32 v120, v119, v118
	v_fma_f32 v121, -v117, v120, v119
	v_fmac_f32_e32 v120, v121, v118
	v_fma_f32 v117, -v117, v120, v119
	v_div_fmas_f32 v117, v117, v118, v120
	v_div_fixup_f32 v116, v117, v116, 1.0
	v_pk_mul_f32 v[50:51], v[50:51], v[116:117] op_sel_hi:[1,0]
	v_pk_mul_f32 v[52:53], v[52:53], v[116:117] op_sel_hi:[1,0]
	v_pk_mul_f32 v[118:119], v[8:9], v[50:51]
	v_pk_mul_f32 v[116:117], v[10:11], v[52:53]
	v_pk_fma_f32 v[52:53], v[10:11], v[52:53], v[56:57]
	v_cvt_pk_f16_f32 v117, v116, v117
	v_cvt_pk_f16_f32 v116, v118, v119
	v_pk_fma_f32 v[50:51], v[8:9], v[50:51], v[54:55]
	global_store_dwordx2 v[62:63], v[116:117], off offset:3840
	ds_write_b128 v163, v[50:53]
	s_waitcnt lgkmcnt(0)
	s_barrier
	s_and_saveexec_b64 s[8:9], s[42:43]
	s_cbranch_execz .LBB0_767
	ds_read2st64_b32 v[52:53], v162 offset1:2
	s_lshl_b32 s2, s12, 4
	s_or_b32 s2, s2, s19
	s_ashr_i32 s3, s2, 31
	s_lshl_b64 s[2:3], s[2:3], 9
	s_waitcnt lgkmcnt(0)
	v_add_f32_e32 v52, 0, v52
	v_add_f32_e32 v54, v52, v53
	ds_read2st64_b32 v[52:53], v162 offset0:4 offset1:6
	v_lshl_add_u64 v[50:51], v[12:13], 0, s[2:3]
	s_waitcnt lgkmcnt(0)
	v_add_f32_e32 v52, v54, v52
	v_add_f32_e32 v54, v52, v53
	ds_read2st64_b32 v[52:53], v162 offset0:8 offset1:10
	s_waitcnt lgkmcnt(0)
	v_add_f32_e32 v52, v54, v52
	v_add_f32_e32 v54, v52, v53
	ds_read2st64_b32 v[52:53], v162 offset0:12 offset1:14
	s_waitcnt lgkmcnt(0)
	v_add_f32_e32 v52, v54, v52
	v_add_f32_e32 v54, v52, v53
	ds_read2st64_b32 v[52:53], v162 offset0:16 offset1:18
	s_waitcnt lgkmcnt(0)
	v_add_f32_e32 v52, v54, v52
	v_add_f32_e32 v54, v52, v53
	ds_read2st64_b32 v[52:53], v162 offset0:20 offset1:22
	s_waitcnt lgkmcnt(0)
	v_add_f32_e32 v52, v54, v52
	v_add_f32_e32 v54, v52, v53
	ds_read2st64_b32 v[52:53], v162 offset0:24 offset1:26
	s_waitcnt lgkmcnt(0)
	v_add_f32_e32 v52, v54, v52
	v_add_f32_e32 v54, v52, v53
	ds_read2st64_b32 v[52:53], v162 offset0:28 offset1:30
	s_waitcnt lgkmcnt(0)
	v_add_f32_e32 v52, v54, v52
	v_add_f32_e32 v52, v52, v53
	v_mul_f32_e32 v52, 0x3b800000, v52
	global_store_dword v[50:51], v52, off
	s_branch .LBB0_767
